# v14 + in-loop LDS-DMA loads in SADDR form (SGPR base + loop-invariant VGPR offsets; 16 address VALU ops per iteration removed) in 6 of 9 GEMM K-loops
# speedup vs baseline: 1.0018x; 1.0018x over previous
.LBB0_291:
	v_mov_b32_e32 v115, 0
	s_andn2_b64 vcc, exec, s[36:37]
	v_mov_b32_e32 v114, v115
	v_mov_b32_e32 v113, v115
	v_mov_b32_e32 v112, v115
	v_mov_b32_e32 v123, v115
	v_mov_b32_e32 v122, v115
	v_mov_b32_e32 v121, v115
	v_mov_b32_e32 v120, v115
	v_mov_b32_e32 v99, v115
	v_mov_b32_e32 v98, v115
	v_mov_b32_e32 v97, v115
	v_mov_b32_e32 v96, v115
	v_mov_b32_e32 v107, v115
	v_mov_b32_e32 v106, v115
	v_mov_b32_e32 v105, v115
	v_mov_b32_e32 v104, v115
	v_mov_b32_e32 v83, v115
	v_mov_b32_e32 v82, v115
	v_mov_b32_e32 v81, v115
	v_mov_b32_e32 v80, v115
	v_mov_b32_e32 v91, v115
	v_mov_b32_e32 v90, v115
	v_mov_b32_e32 v89, v115
	v_mov_b32_e32 v88, v115
	v_mov_b32_e32 v67, v115
	v_mov_b32_e32 v66, v115
	v_mov_b32_e32 v65, v115
	v_mov_b32_e32 v64, v115
	v_mov_b32_e32 v75, v115
	v_mov_b32_e32 v74, v115
	v_mov_b32_e32 v73, v115
	v_mov_b32_e32 v72, v115
	v_mov_b32_e32 v119, v115
	v_mov_b32_e32 v118, v115
	v_mov_b32_e32 v117, v115
	v_mov_b32_e32 v116, v115
	v_mov_b32_e32 v127, v115
	v_mov_b32_e32 v126, v115
	v_mov_b32_e32 v125, v115
	v_mov_b32_e32 v124, v115
	v_mov_b32_e32 v103, v115
	v_mov_b32_e32 v102, v115
	v_mov_b32_e32 v101, v115
	v_mov_b32_e32 v100, v115
	v_mov_b32_e32 v111, v115
	v_mov_b32_e32 v110, v115
	v_mov_b32_e32 v109, v115
	v_mov_b32_e32 v108, v115
	v_mov_b32_e32 v87, v115
	v_mov_b32_e32 v86, v115
	v_mov_b32_e32 v85, v115
	v_mov_b32_e32 v84, v115
	v_mov_b32_e32 v95, v115
	v_mov_b32_e32 v94, v115
	v_mov_b32_e32 v93, v115
	v_mov_b32_e32 v92, v115
	v_mov_b32_e32 v71, v115
	v_mov_b32_e32 v70, v115
	v_mov_b32_e32 v69, v115
	v_mov_b32_e32 v68, v115
	v_mov_b32_e32 v79, v115
	v_mov_b32_e32 v78, v115
	v_mov_b32_e32 v77, v115
	v_mov_b32_e32 v76, v115
	v_mov_b32_e32 v51, v115
	v_mov_b32_e32 v50, v115
	v_mov_b32_e32 v49, v115
	v_mov_b32_e32 v48, v115
	v_mov_b32_e32 v59, v115
	v_mov_b32_e32 v58, v115
	v_mov_b32_e32 v57, v115
	v_mov_b32_e32 v56, v115
	v_mov_b32_e32 v35, v115
	v_mov_b32_e32 v34, v115
	v_mov_b32_e32 v33, v115
	v_mov_b32_e32 v32, v115
	v_mov_b32_e32 v43, v115
	v_mov_b32_e32 v42, v115
	v_mov_b32_e32 v41, v115
	v_mov_b32_e32 v40, v115
	v_mov_b32_e32 v19, v115
	v_mov_b32_e32 v18, v115
	v_mov_b32_e32 v17, v115
	v_mov_b32_e32 v16, v115
	v_mov_b32_e32 v27, v115
	v_mov_b32_e32 v26, v115
	v_mov_b32_e32 v25, v115
	v_mov_b32_e32 v24, v115
	v_mov_b32_e32 v3, v115
	v_mov_b32_e32 v2, v115
	v_mov_b32_e32 v1, v115
	v_mov_b32_e32 v0, v115
	v_mov_b32_e32 v15, v115
	v_mov_b32_e32 v14, v115
	v_mov_b32_e32 v13, v115
	v_mov_b32_e32 v12, v115
	v_mov_b32_e32 v55, v115
	v_mov_b32_e32 v54, v115
	v_mov_b32_e32 v53, v115
	v_mov_b32_e32 v52, v115
	v_mov_b32_e32 v63, v115
	v_mov_b32_e32 v62, v115
	v_mov_b32_e32 v61, v115
	v_mov_b32_e32 v60, v115
	v_mov_b32_e32 v39, v115
	v_mov_b32_e32 v38, v115
	v_mov_b32_e32 v37, v115
	v_mov_b32_e32 v36, v115
	v_mov_b32_e32 v47, v115
	v_mov_b32_e32 v46, v115
	v_mov_b32_e32 v45, v115
	v_mov_b32_e32 v44, v115
	v_mov_b32_e32 v23, v115
	v_mov_b32_e32 v22, v115
	v_mov_b32_e32 v21, v115
	v_mov_b32_e32 v20, v115
	v_mov_b32_e32 v31, v115
	v_mov_b32_e32 v30, v115
	v_mov_b32_e32 v29, v115
	v_mov_b32_e32 v28, v115
	v_mov_b32_e32 v7, v115
	v_mov_b32_e32 v6, v115
	v_mov_b32_e32 v5, v115
	v_mov_b32_e32 v4, v115
	v_mov_b32_e32 v11, v115
	v_mov_b32_e32 v10, v115
	v_mov_b32_e32 v9, v115
	v_mov_b32_e32 v8, v115
	s_cbranch_vccnz .LBB0_294
	s_add_u32 s40, s42, 0x80
	s_addc_u32 s41, s43, 0
	s_add_u32 s33, s28, 0x100
	v_mov_b32_e32 v8, 0
	s_addc_u32 s42, s29, 0
	s_mov_b32 s28, 0
	v_mov_b32_e32 v9, v8
	v_mov_b32_e32 v10, v8
	v_mov_b32_e32 v11, v8
	v_mov_b32_e32 v4, v8
	v_mov_b32_e32 v5, v8
	v_mov_b32_e32 v6, v8
	v_mov_b32_e32 v7, v8
	v_mov_b32_e32 v28, v8
	v_mov_b32_e32 v29, v8
	v_mov_b32_e32 v30, v8
	v_mov_b32_e32 v31, v8
	v_mov_b32_e32 v20, v8
	v_mov_b32_e32 v21, v8
	v_mov_b32_e32 v22, v8
	v_mov_b32_e32 v23, v8
	v_mov_b32_e32 v44, v8
	v_mov_b32_e32 v45, v8
	v_mov_b32_e32 v46, v8
	v_mov_b32_e32 v47, v8
	v_mov_b32_e32 v36, v8
	v_mov_b32_e32 v37, v8
	v_mov_b32_e32 v38, v8
	v_mov_b32_e32 v39, v8
	v_mov_b32_e32 v60, v8
	v_mov_b32_e32 v61, v8
	v_mov_b32_e32 v62, v8
	v_mov_b32_e32 v63, v8
	v_mov_b32_e32 v52, v8
	v_mov_b32_e32 v53, v8
	v_mov_b32_e32 v54, v8
	v_mov_b32_e32 v55, v8
	v_mov_b32_e32 v12, v8
	v_mov_b32_e32 v13, v8
	v_mov_b32_e32 v14, v8
	v_mov_b32_e32 v15, v8
	v_mov_b32_e32 v0, v8
	v_mov_b32_e32 v1, v8
	v_mov_b32_e32 v2, v8
	v_mov_b32_e32 v3, v8
	v_mov_b32_e32 v24, v8
	v_mov_b32_e32 v25, v8
	v_mov_b32_e32 v26, v8
	v_mov_b32_e32 v27, v8
	v_mov_b32_e32 v16, v8
	v_mov_b32_e32 v17, v8
	v_mov_b32_e32 v18, v8
	v_mov_b32_e32 v19, v8
	v_mov_b32_e32 v40, v8
	v_mov_b32_e32 v41, v8
	v_mov_b32_e32 v42, v8
	v_mov_b32_e32 v43, v8
	v_mov_b32_e32 v32, v8
	v_mov_b32_e32 v33, v8
	v_mov_b32_e32 v34, v8
	v_mov_b32_e32 v35, v8
	v_mov_b32_e32 v56, v8
	v_mov_b32_e32 v57, v8
	v_mov_b32_e32 v58, v8
	v_mov_b32_e32 v59, v8
	v_mov_b32_e32 v48, v8
	v_mov_b32_e32 v49, v8
	v_mov_b32_e32 v50, v8
	v_mov_b32_e32 v51, v8
	v_mov_b32_e32 v76, v8
	v_mov_b32_e32 v77, v8
	v_mov_b32_e32 v78, v8
	v_mov_b32_e32 v79, v8
	v_mov_b32_e32 v68, v8
	v_mov_b32_e32 v69, v8
	v_mov_b32_e32 v70, v8
	v_mov_b32_e32 v71, v8
	v_mov_b32_e32 v92, v8
	v_mov_b32_e32 v93, v8
	v_mov_b32_e32 v94, v8
	v_mov_b32_e32 v95, v8
	v_mov_b32_e32 v84, v8
	v_mov_b32_e32 v85, v8
	v_mov_b32_e32 v86, v8
	v_mov_b32_e32 v87, v8
	v_mov_b32_e32 v108, v8
	v_mov_b32_e32 v109, v8
	v_mov_b32_e32 v110, v8
	v_mov_b32_e32 v111, v8
	v_mov_b32_e32 v100, v8
	v_mov_b32_e32 v101, v8
	v_mov_b32_e32 v102, v8
	v_mov_b32_e32 v103, v8
	v_mov_b32_e32 v124, v8
	v_mov_b32_e32 v125, v8
	v_mov_b32_e32 v126, v8
	v_mov_b32_e32 v127, v8
	v_mov_b32_e32 v116, v8
	v_mov_b32_e32 v117, v8
	v_mov_b32_e32 v118, v8
	v_mov_b32_e32 v119, v8
	v_mov_b32_e32 v72, v8
	v_mov_b32_e32 v73, v8
	v_mov_b32_e32 v74, v8
	v_mov_b32_e32 v75, v8
	v_mov_b32_e32 v64, v8
	v_mov_b32_e32 v65, v8
	v_mov_b32_e32 v66, v8
	v_mov_b32_e32 v67, v8
	v_mov_b32_e32 v88, v8
	v_mov_b32_e32 v89, v8
	v_mov_b32_e32 v90, v8
	v_mov_b32_e32 v91, v8
	v_mov_b32_e32 v80, v8
	v_mov_b32_e32 v81, v8
	v_mov_b32_e32 v82, v8
	v_mov_b32_e32 v83, v8
	v_mov_b32_e32 v104, v8
	v_mov_b32_e32 v105, v8
	v_mov_b32_e32 v106, v8
	v_mov_b32_e32 v107, v8
	v_mov_b32_e32 v96, v8
	v_mov_b32_e32 v97, v8
	v_mov_b32_e32 v98, v8
	v_mov_b32_e32 v99, v8
	v_mov_b32_e32 v120, v8
	v_mov_b32_e32 v121, v8
	v_mov_b32_e32 v122, v8
	v_mov_b32_e32 v123, v8
	v_mov_b32_e32 v112, v8
	v_mov_b32_e32 v113, v8
	v_mov_b32_e32 v114, v8
	v_mov_b32_e32 v115, v8
	v_add_u32_e32 v178, s14, v150
	v_add_u32_e32 v179, s14, v154
	v_add_u32_e32 v218, s14, v148
	v_add_u32_e32 v219, s14, v152
	v_add_u32_e32 v220, 128, v150
	v_add_u32_e32 v221, 128, v154
	v_add_u32_e32 v222, 128, v178
	v_add_u32_e32 v223, 128, v179
	v_add_u32_e32 v224, 128, v148
	v_add_u32_e32 v225, 128, v152
.LBB0_293:
	s_add_i32 s43, s28, 2
	s_add_u32 s53, s40, 0x80
	s_addc_u32 s29, s41, 0
	s_add_i32 s72, 0, 0x10000
	s_cmp_eq_u32 s49, s28
	s_cselect_b32 s29, s61, s29
	s_cselect_b32 s28, s60, s53
	v_add_u32_e32 v128, s72, v181
	s_cselect_b32 s71, s65, s42
	s_cselect_b32 s70, s64, s33
	s_add_i32 s53, 0, 0x14000
	ds_read_b128 v[130:133], v128
	ds_read_b128 v[134:137], v128 offset:1024
	ds_read_b128 v[138:141], v128 offset:2048
	ds_read_b128 v[142:145], v128 offset:3072
	v_add_u32_e32 v128, s53, v181
	s_waitcnt lgkmcnt(0)
	ds_read_b128 v[162:165], v128
	ds_read_b128 v[166:169], v128 offset:1024
	ds_read_b128 v[170:173], v128 offset:2048
	ds_read_b128 v[174:177], v128 offset:3072
	s_add_i32 m0, s90, 0xc000
	ds_read_b128 v[186:189], v183
	ds_read_b128 v[190:193], v183 offset:1024
	ds_read_b128 v[194:197], v183 offset:2048
	ds_read_b128 v[198:201], v183 offset:3072
	ds_read_b128 v[202:205], v183 offset:4096
	ds_read_b128 v[206:209], v183 offset:5120
	ds_read_b128 v[210:213], v183 offset:6144
	ds_read_b128 v[214:217], v183 offset:7168
	global_load_lds_dwordx4 v158, s[40:41]
	s_add_i32 m0, s90, 0xe000
	s_nop 0
	global_load_lds_dwordx4 v160, s[40:41]
	s_waitcnt vmcnt(8)
	s_waitcnt lgkmcnt(0)
	s_barrier
	s_setprio 1
	s_waitcnt lgkmcnt(0)
	v_mfma_f32_16x16x32_bf16 v[112:115], v[130:133], v[186:189], v[112:115]
	v_mfma_f32_16x16x32_bf16 v[120:123], v[138:141], v[186:189], v[120:123]
	v_mfma_f32_16x16x32_bf16 v[96:99], v[130:133], v[194:197], v[96:99]
	v_mfma_f32_16x16x32_bf16 v[104:107], v[138:141], v[194:197], v[104:107]
	v_mfma_f32_16x16x32_bf16 v[80:83], v[130:133], v[202:205], v[80:83]
	v_mfma_f32_16x16x32_bf16 v[88:91], v[138:141], v[202:205], v[88:91]
	v_mfma_f32_16x16x32_bf16 v[64:67], v[130:133], v[210:213], v[64:67]
	v_mfma_f32_16x16x32_bf16 v[72:75], v[138:141], v[210:213], v[72:75]
	v_mfma_f32_16x16x32_bf16 v[112:115], v[134:137], v[190:193], v[112:115]
	v_mfma_f32_16x16x32_bf16 v[120:123], v[142:145], v[190:193], v[120:123]
	v_mfma_f32_16x16x32_bf16 v[96:99], v[134:137], v[198:201], v[96:99]
	v_mfma_f32_16x16x32_bf16 v[104:107], v[142:145], v[198:201], v[104:107]
	v_mfma_f32_16x16x32_bf16 v[80:83], v[134:137], v[206:209], v[80:83]
	v_mfma_f32_16x16x32_bf16 v[88:91], v[142:145], v[206:209], v[88:91]
	v_mfma_f32_16x16x32_bf16 v[64:67], v[134:137], v[214:217], v[64:67]
	v_mfma_f32_16x16x32_bf16 v[72:75], v[142:145], v[214:217], v[72:75]
	s_setprio 0
	s_setprio 1
	v_mfma_f32_16x16x32_bf16 v[116:119], v[162:165], v[186:189], v[116:119]
	v_mfma_f32_16x16x32_bf16 v[124:127], v[170:173], v[186:189], v[124:127]
	v_mfma_f32_16x16x32_bf16 v[100:103], v[162:165], v[194:197], v[100:103]
	v_mfma_f32_16x16x32_bf16 v[108:111], v[170:173], v[194:197], v[108:111]
	v_mfma_f32_16x16x32_bf16 v[84:87], v[162:165], v[202:205], v[84:87]
	v_mfma_f32_16x16x32_bf16 v[92:95], v[170:173], v[202:205], v[92:95]
	v_mfma_f32_16x16x32_bf16 v[68:71], v[162:165], v[210:213], v[68:71]
	v_mfma_f32_16x16x32_bf16 v[76:79], v[170:173], v[210:213], v[76:79]
	v_mfma_f32_16x16x32_bf16 v[116:119], v[166:169], v[190:193], v[116:119]
	v_mfma_f32_16x16x32_bf16 v[124:127], v[174:177], v[190:193], v[124:127]
	v_mfma_f32_16x16x32_bf16 v[100:103], v[166:169], v[198:201], v[100:103]
	v_mfma_f32_16x16x32_bf16 v[108:111], v[174:177], v[198:201], v[108:111]
	v_mfma_f32_16x16x32_bf16 v[84:87], v[166:169], v[206:209], v[84:87]
	v_mfma_f32_16x16x32_bf16 v[92:95], v[174:177], v[206:209], v[92:95]
	v_mfma_f32_16x16x32_bf16 v[68:71], v[166:169], v[214:217], v[68:71]
	v_mfma_f32_16x16x32_bf16 v[76:79], v[174:177], v[214:217], v[76:79]
	s_setprio 0
	s_barrier
	s_add_i32 s72, s72, s87
	s_mov_b32 m0, s72
	ds_read_b128 v[186:189], v183 offset:16384
	ds_read_b128 v[190:193], v183 offset:17408
	ds_read_b128 v[194:197], v183 offset:18432
	ds_read_b128 v[198:201], v183 offset:19456
	ds_read_b128 v[202:205], v183 offset:20480
	ds_read_b128 v[206:209], v183 offset:21504
	ds_read_b128 v[210:213], v183 offset:22528
	ds_read_b128 v[214:217], v183 offset:23552
	global_load_lds_dwordx4 v150, s[70:71]
	s_add_i32 m0, s72, 0x2000
	s_add_i32 s53, s53, s87
	global_load_lds_dwordx4 v154, s[70:71]
	s_mov_b32 m0, s53
	s_nop 0
	global_load_lds_dwordx4 v178, s[70:71]
	s_add_i32 m0, s53, 0x2000
	s_nop 0
	global_load_lds_dwordx4 v179, s[70:71]
	s_mov_b32 m0, s90
	s_nop 0
	global_load_lds_dwordx4 v148, s[28:29]
	s_mov_b32 m0, s91
	s_nop 0
	global_load_lds_dwordx4 v152, s[28:29]
	s_waitcnt vmcnt(8)
	s_waitcnt lgkmcnt(0)
	s_barrier
	s_setprio 1
	s_waitcnt lgkmcnt(0)
	v_mfma_f32_16x16x32_bf16 v[48:51], v[130:133], v[186:189], v[48:51]
	v_mfma_f32_16x16x32_bf16 v[56:59], v[138:141], v[186:189], v[56:59]
	v_mfma_f32_16x16x32_bf16 v[32:35], v[130:133], v[194:197], v[32:35]
	v_mfma_f32_16x16x32_bf16 v[40:43], v[138:141], v[194:197], v[40:43]
	v_mfma_f32_16x16x32_bf16 v[16:19], v[130:133], v[202:205], v[16:19]
	v_mfma_f32_16x16x32_bf16 v[24:27], v[138:141], v[202:205], v[24:27]
	v_mfma_f32_16x16x32_bf16 v[0:3], v[130:133], v[210:213], v[0:3]
	v_mfma_f32_16x16x32_bf16 v[12:15], v[138:141], v[210:213], v[12:15]
	v_mfma_f32_16x16x32_bf16 v[48:51], v[134:137], v[190:193], v[48:51]
	v_mfma_f32_16x16x32_bf16 v[56:59], v[142:145], v[190:193], v[56:59]
	v_mfma_f32_16x16x32_bf16 v[32:35], v[134:137], v[198:201], v[32:35]
	v_mfma_f32_16x16x32_bf16 v[40:43], v[142:145], v[198:201], v[40:43]
	v_mfma_f32_16x16x32_bf16 v[16:19], v[134:137], v[206:209], v[16:19]
	v_mfma_f32_16x16x32_bf16 v[24:27], v[142:145], v[206:209], v[24:27]
	v_mfma_f32_16x16x32_bf16 v[0:3], v[134:137], v[214:217], v[0:3]
	v_mfma_f32_16x16x32_bf16 v[12:15], v[142:145], v[214:217], v[12:15]
	s_setprio 0
	s_setprio 1
	v_mfma_f32_16x16x32_bf16 v[52:55], v[162:165], v[186:189], v[52:55]
	v_mfma_f32_16x16x32_bf16 v[60:63], v[170:173], v[186:189], v[60:63]
	v_mfma_f32_16x16x32_bf16 v[36:39], v[162:165], v[194:197], v[36:39]
	v_mfma_f32_16x16x32_bf16 v[44:47], v[170:173], v[194:197], v[44:47]
	v_mfma_f32_16x16x32_bf16 v[20:23], v[162:165], v[202:205], v[20:23]
	v_mfma_f32_16x16x32_bf16 v[28:31], v[170:173], v[202:205], v[28:31]
	v_mfma_f32_16x16x32_bf16 v[4:7], v[162:165], v[210:213], v[4:7]
	v_mfma_f32_16x16x32_bf16 v[8:11], v[170:173], v[210:213], v[8:11]
	v_mfma_f32_16x16x32_bf16 v[52:55], v[166:169], v[190:193], v[52:55]
	v_mfma_f32_16x16x32_bf16 v[60:63], v[174:177], v[190:193], v[60:63]
	v_mfma_f32_16x16x32_bf16 v[36:39], v[166:169], v[198:201], v[36:39]
	v_mfma_f32_16x16x32_bf16 v[44:47], v[174:177], v[198:201], v[44:47]
	v_mfma_f32_16x16x32_bf16 v[20:23], v[166:169], v[206:209], v[20:23]
	v_mfma_f32_16x16x32_bf16 v[28:31], v[174:177], v[206:209], v[28:31]
	v_mfma_f32_16x16x32_bf16 v[4:7], v[166:169], v[214:217], v[4:7]
	v_mfma_f32_16x16x32_bf16 v[8:11], v[174:177], v[214:217], v[8:11]
	s_setprio 0
	s_barrier
	s_add_i32 s53, 0, 0x18000
	v_add_u32_e32 v128, s53, v181
	s_add_i32 s101, 0, 0x1c000
	ds_read_b128 v[130:133], v128
	ds_read_b128 v[134:137], v128 offset:1024
	ds_read_b128 v[138:141], v128 offset:2048
	ds_read_b128 v[142:145], v128 offset:3072
	v_add_u32_e32 v128, s101, v181
	ds_read_b128 v[162:165], v128
	ds_read_b128 v[166:169], v128 offset:1024
	ds_read_b128 v[170:173], v128 offset:2048
	ds_read_b128 v[174:177], v128 offset:3072
	s_mov_b32 m0, s92
	ds_read_b128 v[186:189], v183 offset:32768
	ds_read_b128 v[190:193], v183 offset:33792
	ds_read_b128 v[194:197], v183 offset:34816
	ds_read_b128 v[198:201], v183 offset:35840
	ds_read_b128 v[202:205], v183 offset:36864
	ds_read_b128 v[206:209], v183 offset:37888
	ds_read_b128 v[210:213], v183 offset:38912
	ds_read_b128 v[214:217], v183 offset:39936
	global_load_lds_dwordx4 v218, s[28:29]
	s_mov_b32 m0, s93
	s_nop 0
	global_load_lds_dwordx4 v219, s[28:29]
	s_waitcnt vmcnt(8)
	s_waitcnt lgkmcnt(0)
	s_barrier
	s_setprio 1
	s_waitcnt lgkmcnt(0)
	v_mfma_f32_16x16x32_bf16 v[112:115], v[130:133], v[186:189], v[112:115]
	v_mfma_f32_16x16x32_bf16 v[120:123], v[138:141], v[186:189], v[120:123]
	v_mfma_f32_16x16x32_bf16 v[96:99], v[130:133], v[194:197], v[96:99]
	v_mfma_f32_16x16x32_bf16 v[104:107], v[138:141], v[194:197], v[104:107]
	v_mfma_f32_16x16x32_bf16 v[80:83], v[130:133], v[202:205], v[80:83]
	v_mfma_f32_16x16x32_bf16 v[88:91], v[138:141], v[202:205], v[88:91]
	v_mfma_f32_16x16x32_bf16 v[64:67], v[130:133], v[210:213], v[64:67]
	v_mfma_f32_16x16x32_bf16 v[72:75], v[138:141], v[210:213], v[72:75]
	v_mfma_f32_16x16x32_bf16 v[112:115], v[134:137], v[190:193], v[112:115]
	v_mfma_f32_16x16x32_bf16 v[120:123], v[142:145], v[190:193], v[120:123]
	v_mfma_f32_16x16x32_bf16 v[96:99], v[134:137], v[198:201], v[96:99]
	v_mfma_f32_16x16x32_bf16 v[104:107], v[142:145], v[198:201], v[104:107]
	v_mfma_f32_16x16x32_bf16 v[80:83], v[134:137], v[206:209], v[80:83]
	v_mfma_f32_16x16x32_bf16 v[88:91], v[142:145], v[206:209], v[88:91]
	v_mfma_f32_16x16x32_bf16 v[64:67], v[134:137], v[214:217], v[64:67]
	v_mfma_f32_16x16x32_bf16 v[72:75], v[142:145], v[214:217], v[72:75]
	s_setprio 0
	s_setprio 1
	v_mfma_f32_16x16x32_bf16 v[116:119], v[162:165], v[186:189], v[116:119]
	v_mfma_f32_16x16x32_bf16 v[124:127], v[170:173], v[186:189], v[124:127]
	v_mfma_f32_16x16x32_bf16 v[100:103], v[162:165], v[194:197], v[100:103]
	v_mfma_f32_16x16x32_bf16 v[108:111], v[170:173], v[194:197], v[108:111]
	v_mfma_f32_16x16x32_bf16 v[84:87], v[162:165], v[202:205], v[84:87]
	v_mfma_f32_16x16x32_bf16 v[92:95], v[170:173], v[202:205], v[92:95]
	v_mfma_f32_16x16x32_bf16 v[68:71], v[162:165], v[210:213], v[68:71]
	v_mfma_f32_16x16x32_bf16 v[76:79], v[170:173], v[210:213], v[76:79]
	v_mfma_f32_16x16x32_bf16 v[116:119], v[166:169], v[190:193], v[116:119]
	v_mfma_f32_16x16x32_bf16 v[124:127], v[174:177], v[190:193], v[124:127]
	v_mfma_f32_16x16x32_bf16 v[100:103], v[166:169], v[198:201], v[100:103]
	v_mfma_f32_16x16x32_bf16 v[108:111], v[174:177], v[198:201], v[108:111]
	v_mfma_f32_16x16x32_bf16 v[84:87], v[166:169], v[206:209], v[84:87]
	v_mfma_f32_16x16x32_bf16 v[92:95], v[174:177], v[206:209], v[92:95]
	v_mfma_f32_16x16x32_bf16 v[68:71], v[166:169], v[214:217], v[68:71]
	v_mfma_f32_16x16x32_bf16 v[76:79], v[174:177], v[214:217], v[76:79]
	s_setprio 0
	s_barrier
	s_add_i32 s100, s53, s87
	s_mov_b32 m0, s100
	ds_read_b128 v[186:189], v183 offset:49152
	ds_read_b128 v[190:193], v183 offset:50176
	ds_read_b128 v[194:197], v183 offset:51200
	ds_read_b128 v[198:201], v183 offset:52224
	ds_read_b128 v[202:205], v183 offset:53248
	ds_read_b128 v[206:209], v183 offset:54272
	ds_read_b128 v[210:213], v183 offset:55296
	ds_read_b128 v[214:217], v183 offset:56320
	global_load_lds_dwordx4 v220, s[70:71]
	s_add_i32 m0, s100, 0x2000
	s_add_i32 s100, s101, s87
	global_load_lds_dwordx4 v221, s[70:71]
	s_mov_b32 m0, s100
	s_nop 0
	global_load_lds_dwordx4 v222, s[70:71]
	s_add_i32 m0, s100, 0x2000
	s_nop 0
	global_load_lds_dwordx4 v223, s[70:71]
	s_mov_b32 m0, s97
	s_nop 0
	global_load_lds_dwordx4 v224, s[28:29]
	s_mov_b32 m0, s48
	s_nop 0
	global_load_lds_dwordx4 v225, s[28:29]
	s_waitcnt vmcnt(8)
	s_waitcnt lgkmcnt(0)
	s_barrier
	s_setprio 1
	s_waitcnt lgkmcnt(0)
	v_mfma_f32_16x16x32_bf16 v[48:51], v[130:133], v[186:189], v[48:51]
	v_mfma_f32_16x16x32_bf16 v[56:59], v[138:141], v[186:189], v[56:59]
	v_mfma_f32_16x16x32_bf16 v[32:35], v[130:133], v[194:197], v[32:35]
	v_mfma_f32_16x16x32_bf16 v[40:43], v[138:141], v[194:197], v[40:43]
	v_mfma_f32_16x16x32_bf16 v[16:19], v[130:133], v[202:205], v[16:19]
	v_mfma_f32_16x16x32_bf16 v[24:27], v[138:141], v[202:205], v[24:27]
	v_mfma_f32_16x16x32_bf16 v[0:3], v[130:133], v[210:213], v[0:3]
	v_mfma_f32_16x16x32_bf16 v[12:15], v[138:141], v[210:213], v[12:15]
	v_mfma_f32_16x16x32_bf16 v[48:51], v[134:137], v[190:193], v[48:51]
	v_mfma_f32_16x16x32_bf16 v[56:59], v[142:145], v[190:193], v[56:59]
	v_mfma_f32_16x16x32_bf16 v[32:35], v[134:137], v[198:201], v[32:35]
	v_mfma_f32_16x16x32_bf16 v[40:43], v[142:145], v[198:201], v[40:43]
	v_mfma_f32_16x16x32_bf16 v[16:19], v[134:137], v[206:209], v[16:19]
	v_mfma_f32_16x16x32_bf16 v[24:27], v[142:145], v[206:209], v[24:27]
	v_mfma_f32_16x16x32_bf16 v[0:3], v[134:137], v[214:217], v[0:3]
	v_mfma_f32_16x16x32_bf16 v[12:15], v[142:145], v[214:217], v[12:15]
	s_setprio 0
	s_setprio 1
	v_mfma_f32_16x16x32_bf16 v[52:55], v[162:165], v[186:189], v[52:55]
	v_mfma_f32_16x16x32_bf16 v[60:63], v[170:173], v[186:189], v[60:63]
	v_mfma_f32_16x16x32_bf16 v[36:39], v[162:165], v[194:197], v[36:39]
	v_mfma_f32_16x16x32_bf16 v[44:47], v[170:173], v[194:197], v[44:47]
	v_mfma_f32_16x16x32_bf16 v[20:23], v[162:165], v[202:205], v[20:23]
	v_mfma_f32_16x16x32_bf16 v[28:31], v[170:173], v[202:205], v[28:31]
	v_mfma_f32_16x16x32_bf16 v[4:7], v[162:165], v[210:213], v[4:7]
	v_mfma_f32_16x16x32_bf16 v[8:11], v[170:173], v[210:213], v[8:11]
	v_mfma_f32_16x16x32_bf16 v[52:55], v[166:169], v[190:193], v[52:55]
	v_mfma_f32_16x16x32_bf16 v[60:63], v[174:177], v[190:193], v[60:63]
	v_mfma_f32_16x16x32_bf16 v[36:39], v[166:169], v[198:201], v[36:39]
	v_mfma_f32_16x16x32_bf16 v[44:47], v[174:177], v[198:201], v[44:47]
	v_mfma_f32_16x16x32_bf16 v[20:23], v[166:169], v[206:209], v[20:23]
	v_mfma_f32_16x16x32_bf16 v[28:31], v[174:177], v[206:209], v[28:31]
	v_mfma_f32_16x16x32_bf16 v[4:7], v[166:169], v[214:217], v[4:7]
	v_mfma_f32_16x16x32_bf16 v[8:11], v[174:177], v[214:217], v[8:11]
	s_setprio 0
	s_barrier
	s_add_u32 s40, s40, 0x100
	s_addc_u32 s41, s41, 0
	s_add_u32 s33, s33, 0x100
	s_addc_u32 s42, s42, 0
	s_cmp_ge_i32 s43, s95
	s_mov_b32 s28, s43
	s_cbranch_scc0 .LBB0_293

.LBB0_762:
	v_mov_b32_e32 v123, 0
	s_andn2_b64 vcc, exec, s[36:37]
	v_mov_b32_e32 v122, v123
	v_mov_b32_e32 v121, v123
	v_mov_b32_e32 v120, v123
	v_mov_b32_e32 v127, v123
	v_mov_b32_e32 v126, v123
	v_mov_b32_e32 v125, v123
	v_mov_b32_e32 v124, v123
	v_mov_b32_e32 v111, v123
	v_mov_b32_e32 v110, v123
	v_mov_b32_e32 v109, v123
	v_mov_b32_e32 v108, v123
	v_mov_b32_e32 v107, v123
	v_mov_b32_e32 v106, v123
	v_mov_b32_e32 v105, v123
	v_mov_b32_e32 v104, v123
	v_mov_b32_e32 v95, v123
	v_mov_b32_e32 v94, v123
	v_mov_b32_e32 v93, v123
	v_mov_b32_e32 v92, v123
	v_mov_b32_e32 v91, v123
	v_mov_b32_e32 v90, v123
	v_mov_b32_e32 v89, v123
	v_mov_b32_e32 v88, v123
	v_mov_b32_e32 v79, v123
	v_mov_b32_e32 v78, v123
	v_mov_b32_e32 v77, v123
	v_mov_b32_e32 v76, v123
	v_mov_b32_e32 v75, v123
	v_mov_b32_e32 v74, v123
	v_mov_b32_e32 v73, v123
	v_mov_b32_e32 v72, v123
	v_mov_b32_e32 v119, v123
	v_mov_b32_e32 v118, v123
	v_mov_b32_e32 v117, v123
	v_mov_b32_e32 v116, v123
	v_mov_b32_e32 v115, v123
	v_mov_b32_e32 v114, v123
	v_mov_b32_e32 v113, v123
	v_mov_b32_e32 v112, v123
	v_mov_b32_e32 v103, v123
	v_mov_b32_e32 v102, v123
	v_mov_b32_e32 v101, v123
	v_mov_b32_e32 v100, v123
	v_mov_b32_e32 v99, v123
	v_mov_b32_e32 v98, v123
	v_mov_b32_e32 v97, v123
	v_mov_b32_e32 v96, v123
	v_mov_b32_e32 v87, v123
	v_mov_b32_e32 v86, v123
	v_mov_b32_e32 v85, v123
	v_mov_b32_e32 v84, v123
	v_mov_b32_e32 v83, v123
	v_mov_b32_e32 v82, v123
	v_mov_b32_e32 v81, v123
	v_mov_b32_e32 v80, v123
	v_mov_b32_e32 v71, v123
	v_mov_b32_e32 v70, v123
	v_mov_b32_e32 v69, v123
	v_mov_b32_e32 v68, v123
	v_mov_b32_e32 v67, v123
	v_mov_b32_e32 v66, v123
	v_mov_b32_e32 v65, v123
	v_mov_b32_e32 v64, v123
	v_mov_b32_e32 v63, v123
	v_mov_b32_e32 v62, v123
	v_mov_b32_e32 v61, v123
	v_mov_b32_e32 v60, v123
	v_mov_b32_e32 v59, v123
	v_mov_b32_e32 v58, v123
	v_mov_b32_e32 v57, v123
	v_mov_b32_e32 v56, v123
	v_mov_b32_e32 v47, v123
	v_mov_b32_e32 v46, v123
	v_mov_b32_e32 v45, v123
	v_mov_b32_e32 v44, v123
	v_mov_b32_e32 v43, v123
	v_mov_b32_e32 v42, v123
	v_mov_b32_e32 v41, v123
	v_mov_b32_e32 v40, v123
	v_mov_b32_e32 v31, v123
	v_mov_b32_e32 v30, v123
	v_mov_b32_e32 v29, v123
	v_mov_b32_e32 v28, v123
	v_mov_b32_e32 v27, v123
	v_mov_b32_e32 v26, v123
	v_mov_b32_e32 v25, v123
	v_mov_b32_e32 v24, v123
	v_mov_b32_e32 v15, v123
	v_mov_b32_e32 v14, v123
	v_mov_b32_e32 v13, v123
	v_mov_b32_e32 v12, v123
	v_mov_b32_e32 v11, v123
	v_mov_b32_e32 v10, v123
	v_mov_b32_e32 v9, v123
	v_mov_b32_e32 v8, v123
	v_mov_b32_e32 v55, v123
	v_mov_b32_e32 v54, v123
	v_mov_b32_e32 v53, v123
	v_mov_b32_e32 v52, v123
	v_mov_b32_e32 v51, v123
	v_mov_b32_e32 v50, v123
	v_mov_b32_e32 v49, v123
	v_mov_b32_e32 v48, v123
	v_mov_b32_e32 v39, v123
	v_mov_b32_e32 v38, v123
	v_mov_b32_e32 v37, v123
	v_mov_b32_e32 v36, v123
	v_mov_b32_e32 v35, v123
	v_mov_b32_e32 v34, v123
	v_mov_b32_e32 v33, v123
	v_mov_b32_e32 v32, v123
	v_mov_b32_e32 v23, v123
	v_mov_b32_e32 v22, v123
	v_mov_b32_e32 v21, v123
	v_mov_b32_e32 v20, v123
	v_mov_b32_e32 v19, v123
	v_mov_b32_e32 v18, v123
	v_mov_b32_e32 v17, v123
	v_mov_b32_e32 v16, v123
	v_mov_b32_e32 v7, v123
	v_mov_b32_e32 v6, v123
	v_mov_b32_e32 v5, v123
	v_mov_b32_e32 v4, v123
	v_mov_b32_e32 v3, v123
	v_mov_b32_e32 v2, v123
	v_mov_b32_e32 v1, v123
	v_mov_b32_e32 v0, v123
	s_cbranch_vccnz .LBB0_766
	s_add_u32 s50, s50, 0x80
	s_addc_u32 s51, s51, 0
	s_add_u32 s33, s28, 0x100
	v_mov_b32_e32 v0, 0
	s_addc_u32 s71, s29, 0
	s_mov_b32 s28, 0
	v_mov_b32_e32 v1, v0
	v_mov_b32_e32 v2, v0
	v_mov_b32_e32 v3, v0
	v_mov_b32_e32 v4, v0
	v_mov_b32_e32 v5, v0
	v_mov_b32_e32 v6, v0
	v_mov_b32_e32 v7, v0
	v_mov_b32_e32 v16, v0
	v_mov_b32_e32 v17, v0
	v_mov_b32_e32 v18, v0
	v_mov_b32_e32 v19, v0
	v_mov_b32_e32 v20, v0
	v_mov_b32_e32 v21, v0
	v_mov_b32_e32 v22, v0
	v_mov_b32_e32 v23, v0
	v_mov_b32_e32 v32, v0
	v_mov_b32_e32 v33, v0
	v_mov_b32_e32 v34, v0
	v_mov_b32_e32 v35, v0
	v_mov_b32_e32 v36, v0
	v_mov_b32_e32 v37, v0
	v_mov_b32_e32 v38, v0
	v_mov_b32_e32 v39, v0
	v_mov_b32_e32 v48, v0
	v_mov_b32_e32 v49, v0
	v_mov_b32_e32 v50, v0
	v_mov_b32_e32 v51, v0
	v_mov_b32_e32 v52, v0
	v_mov_b32_e32 v53, v0
	v_mov_b32_e32 v54, v0
	v_mov_b32_e32 v55, v0
	v_mov_b32_e32 v8, v0
	v_mov_b32_e32 v9, v0
	v_mov_b32_e32 v10, v0
	v_mov_b32_e32 v11, v0
	v_mov_b32_e32 v12, v0
	v_mov_b32_e32 v13, v0
	v_mov_b32_e32 v14, v0
	v_mov_b32_e32 v15, v0
	v_mov_b32_e32 v24, v0
	v_mov_b32_e32 v25, v0
	v_mov_b32_e32 v26, v0
	v_mov_b32_e32 v27, v0
	v_mov_b32_e32 v28, v0
	v_mov_b32_e32 v29, v0
	v_mov_b32_e32 v30, v0
	v_mov_b32_e32 v31, v0
	v_mov_b32_e32 v40, v0
	v_mov_b32_e32 v41, v0
	v_mov_b32_e32 v42, v0
	v_mov_b32_e32 v43, v0
	v_mov_b32_e32 v44, v0
	v_mov_b32_e32 v45, v0
	v_mov_b32_e32 v46, v0
	v_mov_b32_e32 v47, v0
	v_mov_b32_e32 v56, v0
	v_mov_b32_e32 v57, v0
	v_mov_b32_e32 v58, v0
	v_mov_b32_e32 v59, v0
	v_mov_b32_e32 v60, v0
	v_mov_b32_e32 v61, v0
	v_mov_b32_e32 v62, v0
	v_mov_b32_e32 v63, v0
	v_mov_b32_e32 v64, v0
	v_mov_b32_e32 v65, v0
	v_mov_b32_e32 v66, v0
	v_mov_b32_e32 v67, v0
	v_mov_b32_e32 v68, v0
	v_mov_b32_e32 v69, v0
	v_mov_b32_e32 v70, v0
	v_mov_b32_e32 v71, v0
	v_mov_b32_e32 v80, v0
	v_mov_b32_e32 v81, v0
	v_mov_b32_e32 v82, v0
	v_mov_b32_e32 v83, v0
	v_mov_b32_e32 v84, v0
	v_mov_b32_e32 v85, v0
	v_mov_b32_e32 v86, v0
	v_mov_b32_e32 v87, v0
	v_mov_b32_e32 v96, v0
	v_mov_b32_e32 v97, v0
	v_mov_b32_e32 v98, v0
	v_mov_b32_e32 v99, v0
	v_mov_b32_e32 v100, v0
	v_mov_b32_e32 v101, v0
	v_mov_b32_e32 v102, v0
	v_mov_b32_e32 v103, v0
	v_mov_b32_e32 v112, v0
	v_mov_b32_e32 v113, v0
	v_mov_b32_e32 v114, v0
	v_mov_b32_e32 v115, v0
	v_mov_b32_e32 v116, v0
	v_mov_b32_e32 v117, v0
	v_mov_b32_e32 v118, v0
	v_mov_b32_e32 v119, v0
	v_mov_b32_e32 v72, v0
	v_mov_b32_e32 v73, v0
	v_mov_b32_e32 v74, v0
	v_mov_b32_e32 v75, v0
	v_mov_b32_e32 v76, v0
	v_mov_b32_e32 v77, v0
	v_mov_b32_e32 v78, v0
	v_mov_b32_e32 v79, v0
	v_mov_b32_e32 v88, v0
	v_mov_b32_e32 v89, v0
	v_mov_b32_e32 v90, v0
	v_mov_b32_e32 v91, v0
	v_mov_b32_e32 v92, v0
	v_mov_b32_e32 v93, v0
	v_mov_b32_e32 v94, v0
	v_mov_b32_e32 v95, v0
	v_mov_b32_e32 v104, v0
	v_mov_b32_e32 v105, v0
	v_mov_b32_e32 v106, v0
	v_mov_b32_e32 v107, v0
	v_mov_b32_e32 v108, v0
	v_mov_b32_e32 v109, v0
	v_mov_b32_e32 v110, v0
	v_mov_b32_e32 v111, v0
	v_mov_b32_e32 v124, v0
	v_mov_b32_e32 v125, v0
	v_mov_b32_e32 v126, v0
	v_mov_b32_e32 v127, v0
	v_mov_b32_e32 v120, v0
	v_mov_b32_e32 v121, v0
	v_mov_b32_e32 v122, v0
	v_mov_b32_e32 v123, v0
	v_add_u32_e32 v142, s22, v132
	v_add_u32_e32 v143, s22, v136
	v_add_u32_e32 v216, s22, v130
	v_add_u32_e32 v217, s22, v134
	v_add_u32_e32 v218, 128, v132
	v_add_u32_e32 v219, 128, v136
	v_add_u32_e32 v220, 128, v142
	v_add_u32_e32 v221, 128, v143
	v_add_u32_e32 v222, 128, v130
	v_add_u32_e32 v223, 128, v134
.LBB0_764:
	s_add_i32 s72, s28, 2
	s_add_u32 s73, s50, 0x80
	s_addc_u32 s29, s51, 0
	s_add_i32 s76, 0, 0x10000
	s_cmp_eq_u32 s58, s28
	s_cselect_b32 s29, s43, s29
	s_cselect_b32 s28, s42, s73
	v_add_u32_e32 v128, s76, v149
	s_cselect_b32 s87, s47, s71
	s_cselect_b32 s86, s46, s33
	s_add_i32 s73, 0, 0x14000
	ds_read_b128 v[152:155], v128
	ds_read_b128 v[156:159], v128 offset:1024
	ds_read_b128 v[160:163], v128 offset:2048
	ds_read_b128 v[164:167], v128 offset:3072
	v_add_u32_e32 v128, s73, v149
	ds_read_b128 v[168:171], v128
	ds_read_b128 v[172:175], v128 offset:1024
	ds_read_b128 v[176:179], v128 offset:2048
	ds_read_b128 v[180:183], v128 offset:3072
	s_add_i32 m0, s20, 0xc000
	ds_read_b128 v[184:187], v151
	ds_read_b128 v[188:191], v151 offset:1024
	ds_read_b128 v[192:195], v151 offset:2048
	ds_read_b128 v[196:199], v151 offset:3072
	ds_read_b128 v[200:203], v151 offset:4096
	ds_read_b128 v[204:207], v151 offset:5120
	ds_read_b128 v[208:211], v151 offset:6144
	ds_read_b128 v[212:215], v151 offset:7168
	global_load_lds_dwordx4 v138, s[50:51]
	s_add_i32 m0, s20, 0xe000
	s_nop 0
	global_load_lds_dwordx4 v140, s[50:51]
	s_waitcnt vmcnt(8)
	s_waitcnt lgkmcnt(0)
	s_barrier
	s_setprio 1
	s_waitcnt lgkmcnt(0)
	v_mfma_f32_16x16x32_bf16 v[120:123], v[152:155], v[184:187], v[120:123]
	v_mfma_f32_16x16x32_bf16 v[124:127], v[160:163], v[184:187], v[124:127]
	v_mfma_f32_16x16x32_bf16 v[108:111], v[152:155], v[192:195], v[108:111]
	v_mfma_f32_16x16x32_bf16 v[104:107], v[160:163], v[192:195], v[104:107]
	v_mfma_f32_16x16x32_bf16 v[92:95], v[152:155], v[200:203], v[92:95]
	v_mfma_f32_16x16x32_bf16 v[88:91], v[160:163], v[200:203], v[88:91]
	v_mfma_f32_16x16x32_bf16 v[76:79], v[152:155], v[208:211], v[76:79]
	v_mfma_f32_16x16x32_bf16 v[72:75], v[160:163], v[208:211], v[72:75]
	v_mfma_f32_16x16x32_bf16 v[120:123], v[156:159], v[188:191], v[120:123]
	v_mfma_f32_16x16x32_bf16 v[124:127], v[164:167], v[188:191], v[124:127]
	v_mfma_f32_16x16x32_bf16 v[108:111], v[156:159], v[196:199], v[108:111]
	v_mfma_f32_16x16x32_bf16 v[104:107], v[164:167], v[196:199], v[104:107]
	v_mfma_f32_16x16x32_bf16 v[92:95], v[156:159], v[204:207], v[92:95]
	v_mfma_f32_16x16x32_bf16 v[88:91], v[164:167], v[204:207], v[88:91]
	v_mfma_f32_16x16x32_bf16 v[76:79], v[156:159], v[212:215], v[76:79]
	v_mfma_f32_16x16x32_bf16 v[72:75], v[164:167], v[212:215], v[72:75]
	s_setprio 0
	s_setprio 1
	v_mfma_f32_16x16x32_bf16 v[116:119], v[168:171], v[184:187], v[116:119]
	v_mfma_f32_16x16x32_bf16 v[112:115], v[176:179], v[184:187], v[112:115]
	v_mfma_f32_16x16x32_bf16 v[100:103], v[168:171], v[192:195], v[100:103]
	v_mfma_f32_16x16x32_bf16 v[96:99], v[176:179], v[192:195], v[96:99]
	v_mfma_f32_16x16x32_bf16 v[84:87], v[168:171], v[200:203], v[84:87]
	v_mfma_f32_16x16x32_bf16 v[80:83], v[176:179], v[200:203], v[80:83]
	v_mfma_f32_16x16x32_bf16 v[68:71], v[168:171], v[208:211], v[68:71]
	v_mfma_f32_16x16x32_bf16 v[64:67], v[176:179], v[208:211], v[64:67]
	v_mfma_f32_16x16x32_bf16 v[116:119], v[172:175], v[188:191], v[116:119]
	v_mfma_f32_16x16x32_bf16 v[112:115], v[180:183], v[188:191], v[112:115]
	v_mfma_f32_16x16x32_bf16 v[100:103], v[172:175], v[196:199], v[100:103]
	v_mfma_f32_16x16x32_bf16 v[96:99], v[180:183], v[196:199], v[96:99]
	v_mfma_f32_16x16x32_bf16 v[84:87], v[172:175], v[204:207], v[84:87]
	v_mfma_f32_16x16x32_bf16 v[80:83], v[180:183], v[204:207], v[80:83]
	v_mfma_f32_16x16x32_bf16 v[68:71], v[172:175], v[212:215], v[68:71]
	v_mfma_f32_16x16x32_bf16 v[64:67], v[180:183], v[212:215], v[64:67]
	s_setprio 0
	s_barrier
	s_add_i32 s76, s76, s18
	s_mov_b32 m0, s76
	ds_read_b128 v[184:187], v151 offset:16384
	ds_read_b128 v[188:191], v151 offset:17408
	ds_read_b128 v[192:195], v151 offset:18432
	ds_read_b128 v[196:199], v151 offset:19456
	ds_read_b128 v[200:203], v151 offset:20480
	ds_read_b128 v[204:207], v151 offset:21504
	ds_read_b128 v[208:211], v151 offset:22528
	ds_read_b128 v[212:215], v151 offset:23552
	global_load_lds_dwordx4 v132, s[86:87]
	s_add_i32 m0, s76, 0x2000
	s_add_i32 s73, s73, s18
	global_load_lds_dwordx4 v136, s[86:87]
	s_mov_b32 m0, s73
	s_nop 0
	global_load_lds_dwordx4 v142, s[86:87]
	s_add_i32 m0, s73, 0x2000
	s_nop 0
	global_load_lds_dwordx4 v143, s[86:87]
	s_mov_b32 m0, s20
	s_nop 0
	global_load_lds_dwordx4 v130, s[28:29]
	s_mov_b32 m0, s48
	s_nop 0
	global_load_lds_dwordx4 v134, s[28:29]
	s_waitcnt vmcnt(8)
	s_waitcnt lgkmcnt(0)
	s_barrier
	s_setprio 1
	s_waitcnt lgkmcnt(0)
	v_mfma_f32_16x16x32_bf16 v[60:63], v[152:155], v[184:187], v[60:63]
	v_mfma_f32_16x16x32_bf16 v[56:59], v[160:163], v[184:187], v[56:59]
	v_mfma_f32_16x16x32_bf16 v[44:47], v[152:155], v[192:195], v[44:47]
	v_mfma_f32_16x16x32_bf16 v[40:43], v[160:163], v[192:195], v[40:43]
	v_mfma_f32_16x16x32_bf16 v[28:31], v[152:155], v[200:203], v[28:31]
	v_mfma_f32_16x16x32_bf16 v[24:27], v[160:163], v[200:203], v[24:27]
	v_mfma_f32_16x16x32_bf16 v[12:15], v[152:155], v[208:211], v[12:15]
	v_mfma_f32_16x16x32_bf16 v[8:11], v[160:163], v[208:211], v[8:11]
	v_mfma_f32_16x16x32_bf16 v[60:63], v[156:159], v[188:191], v[60:63]
	v_mfma_f32_16x16x32_bf16 v[56:59], v[164:167], v[188:191], v[56:59]
	v_mfma_f32_16x16x32_bf16 v[44:47], v[156:159], v[196:199], v[44:47]
	v_mfma_f32_16x16x32_bf16 v[40:43], v[164:167], v[196:199], v[40:43]
	v_mfma_f32_16x16x32_bf16 v[28:31], v[156:159], v[204:207], v[28:31]
	v_mfma_f32_16x16x32_bf16 v[24:27], v[164:167], v[204:207], v[24:27]
	v_mfma_f32_16x16x32_bf16 v[12:15], v[156:159], v[212:215], v[12:15]
	v_mfma_f32_16x16x32_bf16 v[8:11], v[164:167], v[212:215], v[8:11]
	s_setprio 0
	s_setprio 1
	v_mfma_f32_16x16x32_bf16 v[52:55], v[168:171], v[184:187], v[52:55]
	v_mfma_f32_16x16x32_bf16 v[48:51], v[176:179], v[184:187], v[48:51]
	v_mfma_f32_16x16x32_bf16 v[36:39], v[168:171], v[192:195], v[36:39]
	v_mfma_f32_16x16x32_bf16 v[32:35], v[176:179], v[192:195], v[32:35]
	v_mfma_f32_16x16x32_bf16 v[20:23], v[168:171], v[200:203], v[20:23]
	v_mfma_f32_16x16x32_bf16 v[16:19], v[176:179], v[200:203], v[16:19]
	v_mfma_f32_16x16x32_bf16 v[4:7], v[168:171], v[208:211], v[4:7]
	v_mfma_f32_16x16x32_bf16 v[0:3], v[176:179], v[208:211], v[0:3]
	v_mfma_f32_16x16x32_bf16 v[52:55], v[172:175], v[188:191], v[52:55]
	v_mfma_f32_16x16x32_bf16 v[48:51], v[180:183], v[188:191], v[48:51]
	v_mfma_f32_16x16x32_bf16 v[36:39], v[172:175], v[196:199], v[36:39]
	v_mfma_f32_16x16x32_bf16 v[32:35], v[180:183], v[196:199], v[32:35]
	v_mfma_f32_16x16x32_bf16 v[20:23], v[172:175], v[204:207], v[20:23]
	v_mfma_f32_16x16x32_bf16 v[16:19], v[180:183], v[204:207], v[16:19]
	v_mfma_f32_16x16x32_bf16 v[4:7], v[172:175], v[212:215], v[4:7]
	v_mfma_f32_16x16x32_bf16 v[0:3], v[180:183], v[212:215], v[0:3]
	s_setprio 0
	s_barrier
	s_add_i32 s73, 0, 0x18000
	v_add_u32_e32 v128, s73, v149
	s_add_i32 s76, 0, 0x1c000
	ds_read_b128 v[152:155], v128
	ds_read_b128 v[156:159], v128 offset:1024
	ds_read_b128 v[160:163], v128 offset:2048
	ds_read_b128 v[164:167], v128 offset:3072
	v_add_u32_e32 v128, s76, v149
	ds_read_b128 v[168:171], v128
	ds_read_b128 v[172:175], v128 offset:1024
	ds_read_b128 v[176:179], v128 offset:2048
	ds_read_b128 v[180:183], v128 offset:3072
	s_mov_b32 m0, s49
	ds_read_b128 v[184:187], v151 offset:32768
	ds_read_b128 v[188:191], v151 offset:33792
	ds_read_b128 v[192:195], v151 offset:34816
	ds_read_b128 v[196:199], v151 offset:35840
	ds_read_b128 v[200:203], v151 offset:36864
	ds_read_b128 v[204:207], v151 offset:37888
	ds_read_b128 v[208:211], v151 offset:38912
	ds_read_b128 v[212:215], v151 offset:39936
	global_load_lds_dwordx4 v216, s[28:29]
	s_mov_b32 m0, s52
	s_nop 0
	global_load_lds_dwordx4 v217, s[28:29]
	s_waitcnt vmcnt(8)
	s_waitcnt lgkmcnt(0)
	s_barrier
	s_setprio 1
	s_waitcnt lgkmcnt(0)
	v_mfma_f32_16x16x32_bf16 v[120:123], v[152:155], v[184:187], v[120:123]
	v_mfma_f32_16x16x32_bf16 v[124:127], v[160:163], v[184:187], v[124:127]
	v_mfma_f32_16x16x32_bf16 v[108:111], v[152:155], v[192:195], v[108:111]
	v_mfma_f32_16x16x32_bf16 v[104:107], v[160:163], v[192:195], v[104:107]
	v_mfma_f32_16x16x32_bf16 v[92:95], v[152:155], v[200:203], v[92:95]
	v_mfma_f32_16x16x32_bf16 v[88:91], v[160:163], v[200:203], v[88:91]
	v_mfma_f32_16x16x32_bf16 v[76:79], v[152:155], v[208:211], v[76:79]
	v_mfma_f32_16x16x32_bf16 v[72:75], v[160:163], v[208:211], v[72:75]
	v_mfma_f32_16x16x32_bf16 v[120:123], v[156:159], v[188:191], v[120:123]
	v_mfma_f32_16x16x32_bf16 v[124:127], v[164:167], v[188:191], v[124:127]
	v_mfma_f32_16x16x32_bf16 v[108:111], v[156:159], v[196:199], v[108:111]
	v_mfma_f32_16x16x32_bf16 v[104:107], v[164:167], v[196:199], v[104:107]
	v_mfma_f32_16x16x32_bf16 v[92:95], v[156:159], v[204:207], v[92:95]
	v_mfma_f32_16x16x32_bf16 v[88:91], v[164:167], v[204:207], v[88:91]
	v_mfma_f32_16x16x32_bf16 v[76:79], v[156:159], v[212:215], v[76:79]
	v_mfma_f32_16x16x32_bf16 v[72:75], v[164:167], v[212:215], v[72:75]
	s_setprio 0
	s_setprio 1
	v_mfma_f32_16x16x32_bf16 v[116:119], v[168:171], v[184:187], v[116:119]
	v_mfma_f32_16x16x32_bf16 v[112:115], v[176:179], v[184:187], v[112:115]
	v_mfma_f32_16x16x32_bf16 v[100:103], v[168:171], v[192:195], v[100:103]
	v_mfma_f32_16x16x32_bf16 v[96:99], v[176:179], v[192:195], v[96:99]
	v_mfma_f32_16x16x32_bf16 v[84:87], v[168:171], v[200:203], v[84:87]
	v_mfma_f32_16x16x32_bf16 v[80:83], v[176:179], v[200:203], v[80:83]
	v_mfma_f32_16x16x32_bf16 v[68:71], v[168:171], v[208:211], v[68:71]
	v_mfma_f32_16x16x32_bf16 v[64:67], v[176:179], v[208:211], v[64:67]
	v_mfma_f32_16x16x32_bf16 v[116:119], v[172:175], v[188:191], v[116:119]
	v_mfma_f32_16x16x32_bf16 v[112:115], v[180:183], v[188:191], v[112:115]
	v_mfma_f32_16x16x32_bf16 v[100:103], v[172:175], v[196:199], v[100:103]
	v_mfma_f32_16x16x32_bf16 v[96:99], v[180:183], v[196:199], v[96:99]
	v_mfma_f32_16x16x32_bf16 v[84:87], v[172:175], v[204:207], v[84:87]
	v_mfma_f32_16x16x32_bf16 v[80:83], v[180:183], v[204:207], v[80:83]
	v_mfma_f32_16x16x32_bf16 v[68:71], v[172:175], v[212:215], v[68:71]
	v_mfma_f32_16x16x32_bf16 v[64:67], v[180:183], v[212:215], v[64:67]
	s_setprio 0
	s_barrier
	s_add_i32 s100, s73, s18
	s_mov_b32 m0, s100
	ds_read_b128 v[184:187], v151 offset:49152
	ds_read_b128 v[188:191], v151 offset:50176
	ds_read_b128 v[192:195], v151 offset:51200
	ds_read_b128 v[196:199], v151 offset:52224
	ds_read_b128 v[200:203], v151 offset:53248
	ds_read_b128 v[204:207], v151 offset:54272
	ds_read_b128 v[208:211], v151 offset:55296
	ds_read_b128 v[212:215], v151 offset:56320
	global_load_lds_dwordx4 v218, s[86:87]
	s_add_i32 m0, s100, 0x2000
	s_add_i32 s100, s76, s18
	global_load_lds_dwordx4 v219, s[86:87]
	s_mov_b32 m0, s100
	s_nop 0
	global_load_lds_dwordx4 v220, s[86:87]
	s_add_i32 m0, s100, 0x2000
	s_nop 0
	global_load_lds_dwordx4 v221, s[86:87]
	s_mov_b32 m0, s53
	s_nop 0
	global_load_lds_dwordx4 v222, s[28:29]
	s_mov_b32 m0, s56
	s_nop 0
	global_load_lds_dwordx4 v223, s[28:29]
	s_waitcnt vmcnt(8)
	s_waitcnt lgkmcnt(0)
	s_barrier
	s_setprio 1
	s_waitcnt lgkmcnt(0)
	v_mfma_f32_16x16x32_bf16 v[60:63], v[152:155], v[184:187], v[60:63]
	v_mfma_f32_16x16x32_bf16 v[56:59], v[160:163], v[184:187], v[56:59]
	v_mfma_f32_16x16x32_bf16 v[44:47], v[152:155], v[192:195], v[44:47]
	v_mfma_f32_16x16x32_bf16 v[40:43], v[160:163], v[192:195], v[40:43]
	v_mfma_f32_16x16x32_bf16 v[28:31], v[152:155], v[200:203], v[28:31]
	v_mfma_f32_16x16x32_bf16 v[24:27], v[160:163], v[200:203], v[24:27]
	v_mfma_f32_16x16x32_bf16 v[12:15], v[152:155], v[208:211], v[12:15]
	v_mfma_f32_16x16x32_bf16 v[8:11], v[160:163], v[208:211], v[8:11]
	v_mfma_f32_16x16x32_bf16 v[60:63], v[156:159], v[188:191], v[60:63]
	v_mfma_f32_16x16x32_bf16 v[56:59], v[164:167], v[188:191], v[56:59]
	v_mfma_f32_16x16x32_bf16 v[44:47], v[156:159], v[196:199], v[44:47]
	v_mfma_f32_16x16x32_bf16 v[40:43], v[164:167], v[196:199], v[40:43]
	v_mfma_f32_16x16x32_bf16 v[28:31], v[156:159], v[204:207], v[28:31]
	v_mfma_f32_16x16x32_bf16 v[24:27], v[164:167], v[204:207], v[24:27]
	v_mfma_f32_16x16x32_bf16 v[12:15], v[156:159], v[212:215], v[12:15]
	v_mfma_f32_16x16x32_bf16 v[8:11], v[164:167], v[212:215], v[8:11]
	s_setprio 0
	s_setprio 1
	v_mfma_f32_16x16x32_bf16 v[52:55], v[168:171], v[184:187], v[52:55]
	v_mfma_f32_16x16x32_bf16 v[48:51], v[176:179], v[184:187], v[48:51]
	v_mfma_f32_16x16x32_bf16 v[36:39], v[168:171], v[192:195], v[36:39]
	v_mfma_f32_16x16x32_bf16 v[32:35], v[176:179], v[192:195], v[32:35]
	v_mfma_f32_16x16x32_bf16 v[20:23], v[168:171], v[200:203], v[20:23]
	v_mfma_f32_16x16x32_bf16 v[16:19], v[176:179], v[200:203], v[16:19]
	v_mfma_f32_16x16x32_bf16 v[4:7], v[168:171], v[208:211], v[4:7]
	v_mfma_f32_16x16x32_bf16 v[0:3], v[176:179], v[208:211], v[0:3]
	v_mfma_f32_16x16x32_bf16 v[52:55], v[172:175], v[188:191], v[52:55]
	v_mfma_f32_16x16x32_bf16 v[48:51], v[180:183], v[188:191], v[48:51]
	v_mfma_f32_16x16x32_bf16 v[36:39], v[172:175], v[196:199], v[36:39]
	v_mfma_f32_16x16x32_bf16 v[32:35], v[180:183], v[196:199], v[32:35]
	v_mfma_f32_16x16x32_bf16 v[20:23], v[172:175], v[204:207], v[20:23]
	v_mfma_f32_16x16x32_bf16 v[16:19], v[180:183], v[204:207], v[16:19]
	v_mfma_f32_16x16x32_bf16 v[4:7], v[172:175], v[212:215], v[4:7]
	v_mfma_f32_16x16x32_bf16 v[0:3], v[180:183], v[212:215], v[0:3]
	s_setprio 0
	s_barrier
	s_add_u32 s50, s50, 0x100
	s_addc_u32 s51, s51, 0
	s_add_u32 s33, s33, 0x100
	s_addc_u32 s71, s71, 0
	s_cmp_ge_i32 s72, s57
	s_mov_b32 s28, s72
	s_cbranch_scc0 .LBB0_764
	v_readlane_b32 s86, v255, 23
	v_readlane_b32 s87, v255, 24
	s_movk_i32 s76, 0x6000

.LBB0_1644:
	v_mov_b32_e32 v123, 0
	s_andn2_b64 vcc, exec, s[26:27]
	v_mov_b32_e32 v122, v123
	v_mov_b32_e32 v121, v123
	v_mov_b32_e32 v120, v123
	v_mov_b32_e32 v127, v123
	v_mov_b32_e32 v126, v123
	v_mov_b32_e32 v125, v123
	v_mov_b32_e32 v124, v123
	v_mov_b32_e32 v111, v123
	v_mov_b32_e32 v110, v123
	v_mov_b32_e32 v109, v123
	v_mov_b32_e32 v108, v123
	v_mov_b32_e32 v107, v123
	v_mov_b32_e32 v106, v123
	v_mov_b32_e32 v105, v123
	v_mov_b32_e32 v104, v123
	v_mov_b32_e32 v95, v123
	v_mov_b32_e32 v94, v123
	v_mov_b32_e32 v93, v123
	v_mov_b32_e32 v92, v123
	v_mov_b32_e32 v91, v123
	v_mov_b32_e32 v90, v123
	v_mov_b32_e32 v89, v123
	v_mov_b32_e32 v88, v123
	v_mov_b32_e32 v79, v123
	v_mov_b32_e32 v78, v123
	v_mov_b32_e32 v77, v123
	v_mov_b32_e32 v76, v123
	v_mov_b32_e32 v75, v123
	v_mov_b32_e32 v74, v123
	v_mov_b32_e32 v73, v123
	v_mov_b32_e32 v72, v123
	v_mov_b32_e32 v119, v123
	v_mov_b32_e32 v118, v123
	v_mov_b32_e32 v117, v123
	v_mov_b32_e32 v116, v123
	v_mov_b32_e32 v115, v123
	v_mov_b32_e32 v114, v123
	v_mov_b32_e32 v113, v123
	v_mov_b32_e32 v112, v123
	v_mov_b32_e32 v103, v123
	v_mov_b32_e32 v102, v123
	v_mov_b32_e32 v101, v123
	v_mov_b32_e32 v100, v123
	v_mov_b32_e32 v99, v123
	v_mov_b32_e32 v98, v123
	v_mov_b32_e32 v97, v123
	v_mov_b32_e32 v96, v123
	v_mov_b32_e32 v87, v123
	v_mov_b32_e32 v86, v123
	v_mov_b32_e32 v85, v123
	v_mov_b32_e32 v84, v123
	v_mov_b32_e32 v83, v123
	v_mov_b32_e32 v82, v123
	v_mov_b32_e32 v81, v123
	v_mov_b32_e32 v80, v123
	v_mov_b32_e32 v71, v123
	v_mov_b32_e32 v70, v123
	v_mov_b32_e32 v69, v123
	v_mov_b32_e32 v68, v123
	v_mov_b32_e32 v67, v123
	v_mov_b32_e32 v66, v123
	v_mov_b32_e32 v65, v123
	v_mov_b32_e32 v64, v123
	v_mov_b32_e32 v63, v123
	v_mov_b32_e32 v62, v123
	v_mov_b32_e32 v61, v123
	v_mov_b32_e32 v60, v123
	v_mov_b32_e32 v59, v123
	v_mov_b32_e32 v58, v123
	v_mov_b32_e32 v57, v123
	v_mov_b32_e32 v56, v123
	v_mov_b32_e32 v47, v123
	v_mov_b32_e32 v46, v123
	v_mov_b32_e32 v45, v123
	v_mov_b32_e32 v44, v123
	v_mov_b32_e32 v43, v123
	v_mov_b32_e32 v42, v123
	v_mov_b32_e32 v41, v123
	v_mov_b32_e32 v40, v123
	v_mov_b32_e32 v31, v123
	v_mov_b32_e32 v30, v123
	v_mov_b32_e32 v29, v123
	v_mov_b32_e32 v28, v123
	v_mov_b32_e32 v27, v123
	v_mov_b32_e32 v26, v123
	v_mov_b32_e32 v25, v123
	v_mov_b32_e32 v24, v123
	v_mov_b32_e32 v15, v123
	v_mov_b32_e32 v14, v123
	v_mov_b32_e32 v13, v123
	v_mov_b32_e32 v12, v123
	v_mov_b32_e32 v11, v123
	v_mov_b32_e32 v10, v123
	v_mov_b32_e32 v9, v123
	v_mov_b32_e32 v8, v123
	v_mov_b32_e32 v55, v123
	v_mov_b32_e32 v54, v123
	v_mov_b32_e32 v53, v123
	v_mov_b32_e32 v52, v123
	v_mov_b32_e32 v51, v123
	v_mov_b32_e32 v50, v123
	v_mov_b32_e32 v49, v123
	v_mov_b32_e32 v48, v123
	v_mov_b32_e32 v39, v123
	v_mov_b32_e32 v38, v123
	v_mov_b32_e32 v37, v123
	v_mov_b32_e32 v36, v123
	v_mov_b32_e32 v35, v123
	v_mov_b32_e32 v34, v123
	v_mov_b32_e32 v33, v123
	v_mov_b32_e32 v32, v123
	v_mov_b32_e32 v23, v123
	v_mov_b32_e32 v22, v123
	v_mov_b32_e32 v21, v123
	v_mov_b32_e32 v20, v123
	v_mov_b32_e32 v19, v123
	v_mov_b32_e32 v18, v123
	v_mov_b32_e32 v17, v123
	v_mov_b32_e32 v16, v123
	v_mov_b32_e32 v7, v123
	v_mov_b32_e32 v6, v123
	v_mov_b32_e32 v5, v123
	v_mov_b32_e32 v4, v123
	v_mov_b32_e32 v3, v123
	v_mov_b32_e32 v2, v123
	v_mov_b32_e32 v1, v123
	v_mov_b32_e32 v0, v123
	s_cbranch_vccnz .LBB0_1648
	s_add_u32 s46, s46, 0x80
	s_addc_u32 s47, s47, 0
	s_add_u32 s33, s28, 0x100
	v_mov_b32_e32 v0, 0
	s_addc_u32 s67, s29, 0
	s_mov_b32 s28, 0
	v_mov_b32_e32 v1, v0
	v_mov_b32_e32 v2, v0
	v_mov_b32_e32 v3, v0
	v_mov_b32_e32 v4, v0
	v_mov_b32_e32 v5, v0
	v_mov_b32_e32 v6, v0
	v_mov_b32_e32 v7, v0
	v_mov_b32_e32 v16, v0
	v_mov_b32_e32 v17, v0
	v_mov_b32_e32 v18, v0
	v_mov_b32_e32 v19, v0
	v_mov_b32_e32 v20, v0
	v_mov_b32_e32 v21, v0
	v_mov_b32_e32 v22, v0
	v_mov_b32_e32 v23, v0
	v_mov_b32_e32 v32, v0
	v_mov_b32_e32 v33, v0
	v_mov_b32_e32 v34, v0
	v_mov_b32_e32 v35, v0
	v_mov_b32_e32 v36, v0
	v_mov_b32_e32 v37, v0
	v_mov_b32_e32 v38, v0
	v_mov_b32_e32 v39, v0
	v_mov_b32_e32 v48, v0
	v_mov_b32_e32 v49, v0
	v_mov_b32_e32 v50, v0
	v_mov_b32_e32 v51, v0
	v_mov_b32_e32 v52, v0
	v_mov_b32_e32 v53, v0
	v_mov_b32_e32 v54, v0
	v_mov_b32_e32 v55, v0
	v_mov_b32_e32 v8, v0
	v_mov_b32_e32 v9, v0
	v_mov_b32_e32 v10, v0
	v_mov_b32_e32 v11, v0
	v_mov_b32_e32 v12, v0
	v_mov_b32_e32 v13, v0
	v_mov_b32_e32 v14, v0
	v_mov_b32_e32 v15, v0
	v_mov_b32_e32 v24, v0
	v_mov_b32_e32 v25, v0
	v_mov_b32_e32 v26, v0
	v_mov_b32_e32 v27, v0
	v_mov_b32_e32 v28, v0
	v_mov_b32_e32 v29, v0
	v_mov_b32_e32 v30, v0
	v_mov_b32_e32 v31, v0
	v_mov_b32_e32 v40, v0
	v_mov_b32_e32 v41, v0
	v_mov_b32_e32 v42, v0
	v_mov_b32_e32 v43, v0
	v_mov_b32_e32 v44, v0
	v_mov_b32_e32 v45, v0
	v_mov_b32_e32 v46, v0
	v_mov_b32_e32 v47, v0
	v_mov_b32_e32 v56, v0
	v_mov_b32_e32 v57, v0
	v_mov_b32_e32 v58, v0
	v_mov_b32_e32 v59, v0
	v_mov_b32_e32 v60, v0
	v_mov_b32_e32 v61, v0
	v_mov_b32_e32 v62, v0
	v_mov_b32_e32 v63, v0
	v_mov_b32_e32 v64, v0
	v_mov_b32_e32 v65, v0
	v_mov_b32_e32 v66, v0
	v_mov_b32_e32 v67, v0
	v_mov_b32_e32 v68, v0
	v_mov_b32_e32 v69, v0
	v_mov_b32_e32 v70, v0
	v_mov_b32_e32 v71, v0
	v_mov_b32_e32 v80, v0
	v_mov_b32_e32 v81, v0
	v_mov_b32_e32 v82, v0
	v_mov_b32_e32 v83, v0
	v_mov_b32_e32 v84, v0
	v_mov_b32_e32 v85, v0
	v_mov_b32_e32 v86, v0
	v_mov_b32_e32 v87, v0
	v_mov_b32_e32 v96, v0
	v_mov_b32_e32 v97, v0
	v_mov_b32_e32 v98, v0
	v_mov_b32_e32 v99, v0
	v_mov_b32_e32 v100, v0
	v_mov_b32_e32 v101, v0
	v_mov_b32_e32 v102, v0
	v_mov_b32_e32 v103, v0
	v_mov_b32_e32 v112, v0
	v_mov_b32_e32 v113, v0
	v_mov_b32_e32 v114, v0
	v_mov_b32_e32 v115, v0
	v_mov_b32_e32 v116, v0
	v_mov_b32_e32 v117, v0
	v_mov_b32_e32 v118, v0
	v_mov_b32_e32 v119, v0
	v_mov_b32_e32 v72, v0
	v_mov_b32_e32 v73, v0
	v_mov_b32_e32 v74, v0
	v_mov_b32_e32 v75, v0
	v_mov_b32_e32 v76, v0
	v_mov_b32_e32 v77, v0
	v_mov_b32_e32 v78, v0
	v_mov_b32_e32 v79, v0
	v_mov_b32_e32 v88, v0
	v_mov_b32_e32 v89, v0
	v_mov_b32_e32 v90, v0
	v_mov_b32_e32 v91, v0
	v_mov_b32_e32 v92, v0
	v_mov_b32_e32 v93, v0
	v_mov_b32_e32 v94, v0
	v_mov_b32_e32 v95, v0
	v_mov_b32_e32 v104, v0
	v_mov_b32_e32 v105, v0
	v_mov_b32_e32 v106, v0
	v_mov_b32_e32 v107, v0
	v_mov_b32_e32 v108, v0
	v_mov_b32_e32 v109, v0
	v_mov_b32_e32 v110, v0
	v_mov_b32_e32 v111, v0
	v_mov_b32_e32 v124, v0
	v_mov_b32_e32 v125, v0
	v_mov_b32_e32 v126, v0
	v_mov_b32_e32 v127, v0
	v_mov_b32_e32 v120, v0
	v_mov_b32_e32 v121, v0
	v_mov_b32_e32 v122, v0
	v_mov_b32_e32 v123, v0
	v_add_u32_e32 v142, s14, v132
	v_add_u32_e32 v143, s14, v136
	v_add_u32_e32 v216, s14, v130
	v_add_u32_e32 v217, s14, v134
	v_add_u32_e32 v218, 128, v132
	v_add_u32_e32 v219, 128, v136
	v_add_u32_e32 v220, 128, v142
	v_add_u32_e32 v221, 128, v143
	v_add_u32_e32 v222, 128, v130
	v_add_u32_e32 v223, 128, v134
.LBB0_1646:
	s_add_i32 s70, s28, 2
	s_add_u32 s71, s46, 0x80
	s_addc_u32 s29, s47, 0
	s_add_i32 s76, 0, 0x10000
	s_cmp_eq_u32 s56, s28
	s_cselect_b32 s29, s43, s29
	s_cselect_b32 s28, s42, s71
	v_add_u32_e32 v128, s76, v149
	s_cselect_b32 s73, s45, s67
	s_cselect_b32 s72, s44, s33
	s_add_i32 s71, 0, 0x14000
	ds_read_b128 v[152:155], v128
	ds_read_b128 v[156:159], v128 offset:1024
	ds_read_b128 v[160:163], v128 offset:2048
	ds_read_b128 v[164:167], v128 offset:3072
	v_add_u32_e32 v128, s71, v149
	ds_read_b128 v[168:171], v128
	ds_read_b128 v[172:175], v128 offset:1024
	ds_read_b128 v[176:179], v128 offset:2048
	ds_read_b128 v[180:183], v128 offset:3072
	s_add_i32 m0, s20, 0xc000
	ds_read_b128 v[184:187], v151
	ds_read_b128 v[188:191], v151 offset:1024
	ds_read_b128 v[192:195], v151 offset:2048
	ds_read_b128 v[196:199], v151 offset:3072
	ds_read_b128 v[200:203], v151 offset:4096
	ds_read_b128 v[204:207], v151 offset:5120
	ds_read_b128 v[208:211], v151 offset:6144
	ds_read_b128 v[212:215], v151 offset:7168
	global_load_lds_dwordx4 v138, s[46:47]
	s_add_i32 m0, s20, 0xe000
	s_nop 0
	global_load_lds_dwordx4 v140, s[46:47]
	s_waitcnt vmcnt(8)
	s_waitcnt lgkmcnt(0)
	s_barrier
	s_setprio 1
	s_waitcnt lgkmcnt(0)
	v_mfma_f32_16x16x32_bf16 v[120:123], v[152:155], v[184:187], v[120:123]
	v_mfma_f32_16x16x32_bf16 v[124:127], v[160:163], v[184:187], v[124:127]
	v_mfma_f32_16x16x32_bf16 v[108:111], v[152:155], v[192:195], v[108:111]
	v_mfma_f32_16x16x32_bf16 v[104:107], v[160:163], v[192:195], v[104:107]
	v_mfma_f32_16x16x32_bf16 v[92:95], v[152:155], v[200:203], v[92:95]
	v_mfma_f32_16x16x32_bf16 v[88:91], v[160:163], v[200:203], v[88:91]
	v_mfma_f32_16x16x32_bf16 v[76:79], v[152:155], v[208:211], v[76:79]
	v_mfma_f32_16x16x32_bf16 v[72:75], v[160:163], v[208:211], v[72:75]
	v_mfma_f32_16x16x32_bf16 v[120:123], v[156:159], v[188:191], v[120:123]
	v_mfma_f32_16x16x32_bf16 v[124:127], v[164:167], v[188:191], v[124:127]
	v_mfma_f32_16x16x32_bf16 v[108:111], v[156:159], v[196:199], v[108:111]
	v_mfma_f32_16x16x32_bf16 v[104:107], v[164:167], v[196:199], v[104:107]
	v_mfma_f32_16x16x32_bf16 v[92:95], v[156:159], v[204:207], v[92:95]
	v_mfma_f32_16x16x32_bf16 v[88:91], v[164:167], v[204:207], v[88:91]
	v_mfma_f32_16x16x32_bf16 v[76:79], v[156:159], v[212:215], v[76:79]
	v_mfma_f32_16x16x32_bf16 v[72:75], v[164:167], v[212:215], v[72:75]
	s_setprio 0
	s_setprio 1
	v_mfma_f32_16x16x32_bf16 v[116:119], v[168:171], v[184:187], v[116:119]
	v_mfma_f32_16x16x32_bf16 v[112:115], v[176:179], v[184:187], v[112:115]
	v_mfma_f32_16x16x32_bf16 v[100:103], v[168:171], v[192:195], v[100:103]
	v_mfma_f32_16x16x32_bf16 v[96:99], v[176:179], v[192:195], v[96:99]
	v_mfma_f32_16x16x32_bf16 v[84:87], v[168:171], v[200:203], v[84:87]
	v_mfma_f32_16x16x32_bf16 v[80:83], v[176:179], v[200:203], v[80:83]
	v_mfma_f32_16x16x32_bf16 v[68:71], v[168:171], v[208:211], v[68:71]
	v_mfma_f32_16x16x32_bf16 v[64:67], v[176:179], v[208:211], v[64:67]
	v_mfma_f32_16x16x32_bf16 v[116:119], v[172:175], v[188:191], v[116:119]
	v_mfma_f32_16x16x32_bf16 v[112:115], v[180:183], v[188:191], v[112:115]
	v_mfma_f32_16x16x32_bf16 v[100:103], v[172:175], v[196:199], v[100:103]
	v_mfma_f32_16x16x32_bf16 v[96:99], v[180:183], v[196:199], v[96:99]
	v_mfma_f32_16x16x32_bf16 v[84:87], v[172:175], v[204:207], v[84:87]
	v_mfma_f32_16x16x32_bf16 v[80:83], v[180:183], v[204:207], v[80:83]
	v_mfma_f32_16x16x32_bf16 v[68:71], v[172:175], v[212:215], v[68:71]
	v_mfma_f32_16x16x32_bf16 v[64:67], v[180:183], v[212:215], v[64:67]
	s_setprio 0
	s_barrier
	s_add_i32 s76, s76, s18
	s_mov_b32 m0, s76
	ds_read_b128 v[184:187], v151 offset:16384
	ds_read_b128 v[188:191], v151 offset:17408
	ds_read_b128 v[192:195], v151 offset:18432
	ds_read_b128 v[196:199], v151 offset:19456
	ds_read_b128 v[200:203], v151 offset:20480
	ds_read_b128 v[204:207], v151 offset:21504
	ds_read_b128 v[208:211], v151 offset:22528
	ds_read_b128 v[212:215], v151 offset:23552
	global_load_lds_dwordx4 v132, s[72:73]
	s_add_i32 m0, s76, 0x2000
	s_add_i32 s71, s71, s18
	global_load_lds_dwordx4 v136, s[72:73]
	s_mov_b32 m0, s71
	s_nop 0
	global_load_lds_dwordx4 v142, s[72:73]
	s_add_i32 m0, s71, 0x2000
	s_nop 0
	global_load_lds_dwordx4 v143, s[72:73]
	s_mov_b32 m0, s20
	s_nop 0
	global_load_lds_dwordx4 v130, s[28:29]
	s_mov_b32 m0, s48
	s_nop 0
	global_load_lds_dwordx4 v134, s[28:29]
	s_waitcnt vmcnt(8)
	s_waitcnt lgkmcnt(0)
	s_barrier
	s_setprio 1
	s_waitcnt lgkmcnt(0)
	v_mfma_f32_16x16x32_bf16 v[60:63], v[152:155], v[184:187], v[60:63]
	v_mfma_f32_16x16x32_bf16 v[56:59], v[160:163], v[184:187], v[56:59]
	v_mfma_f32_16x16x32_bf16 v[44:47], v[152:155], v[192:195], v[44:47]
	v_mfma_f32_16x16x32_bf16 v[40:43], v[160:163], v[192:195], v[40:43]
	v_mfma_f32_16x16x32_bf16 v[28:31], v[152:155], v[200:203], v[28:31]
	v_mfma_f32_16x16x32_bf16 v[24:27], v[160:163], v[200:203], v[24:27]
	v_mfma_f32_16x16x32_bf16 v[12:15], v[152:155], v[208:211], v[12:15]
	v_mfma_f32_16x16x32_bf16 v[8:11], v[160:163], v[208:211], v[8:11]
	v_mfma_f32_16x16x32_bf16 v[60:63], v[156:159], v[188:191], v[60:63]
	v_mfma_f32_16x16x32_bf16 v[56:59], v[164:167], v[188:191], v[56:59]
	v_mfma_f32_16x16x32_bf16 v[44:47], v[156:159], v[196:199], v[44:47]
	v_mfma_f32_16x16x32_bf16 v[40:43], v[164:167], v[196:199], v[40:43]
	v_mfma_f32_16x16x32_bf16 v[28:31], v[156:159], v[204:207], v[28:31]
	v_mfma_f32_16x16x32_bf16 v[24:27], v[164:167], v[204:207], v[24:27]
	v_mfma_f32_16x16x32_bf16 v[12:15], v[156:159], v[212:215], v[12:15]
	v_mfma_f32_16x16x32_bf16 v[8:11], v[164:167], v[212:215], v[8:11]
	s_setprio 0
	s_setprio 1
	v_mfma_f32_16x16x32_bf16 v[52:55], v[168:171], v[184:187], v[52:55]
	v_mfma_f32_16x16x32_bf16 v[48:51], v[176:179], v[184:187], v[48:51]
	v_mfma_f32_16x16x32_bf16 v[36:39], v[168:171], v[192:195], v[36:39]
	v_mfma_f32_16x16x32_bf16 v[32:35], v[176:179], v[192:195], v[32:35]
	v_mfma_f32_16x16x32_bf16 v[20:23], v[168:171], v[200:203], v[20:23]
	v_mfma_f32_16x16x32_bf16 v[16:19], v[176:179], v[200:203], v[16:19]
	v_mfma_f32_16x16x32_bf16 v[4:7], v[168:171], v[208:211], v[4:7]
	v_mfma_f32_16x16x32_bf16 v[0:3], v[176:179], v[208:211], v[0:3]
	v_mfma_f32_16x16x32_bf16 v[52:55], v[172:175], v[188:191], v[52:55]
	v_mfma_f32_16x16x32_bf16 v[48:51], v[180:183], v[188:191], v[48:51]
	v_mfma_f32_16x16x32_bf16 v[36:39], v[172:175], v[196:199], v[36:39]
	v_mfma_f32_16x16x32_bf16 v[32:35], v[180:183], v[196:199], v[32:35]
	v_mfma_f32_16x16x32_bf16 v[20:23], v[172:175], v[204:207], v[20:23]
	v_mfma_f32_16x16x32_bf16 v[16:19], v[180:183], v[204:207], v[16:19]
	v_mfma_f32_16x16x32_bf16 v[4:7], v[172:175], v[212:215], v[4:7]
	v_mfma_f32_16x16x32_bf16 v[0:3], v[180:183], v[212:215], v[0:3]
	s_setprio 0
	s_barrier
	s_add_i32 s71, 0, 0x18000
	v_add_u32_e32 v128, s71, v149
	s_add_i32 s101, 0, 0x1c000
	ds_read_b128 v[152:155], v128
	ds_read_b128 v[156:159], v128 offset:1024
	ds_read_b128 v[160:163], v128 offset:2048
	ds_read_b128 v[164:167], v128 offset:3072
	v_add_u32_e32 v128, s101, v149
	ds_read_b128 v[168:171], v128
	ds_read_b128 v[172:175], v128 offset:1024
	ds_read_b128 v[176:179], v128 offset:2048
	ds_read_b128 v[180:183], v128 offset:3072
	s_mov_b32 m0, s49
	ds_read_b128 v[184:187], v151 offset:32768
	ds_read_b128 v[188:191], v151 offset:33792
	ds_read_b128 v[192:195], v151 offset:34816
	ds_read_b128 v[196:199], v151 offset:35840
	ds_read_b128 v[200:203], v151 offset:36864
	ds_read_b128 v[204:207], v151 offset:37888
	ds_read_b128 v[208:211], v151 offset:38912
	ds_read_b128 v[212:215], v151 offset:39936
	global_load_lds_dwordx4 v216, s[28:29]
	s_mov_b32 m0, s50
	s_nop 0
	global_load_lds_dwordx4 v217, s[28:29]
	s_waitcnt vmcnt(8)
	s_waitcnt lgkmcnt(0)
	s_barrier
	s_setprio 1
	s_waitcnt lgkmcnt(0)
	v_mfma_f32_16x16x32_bf16 v[120:123], v[152:155], v[184:187], v[120:123]
	v_mfma_f32_16x16x32_bf16 v[124:127], v[160:163], v[184:187], v[124:127]
	v_mfma_f32_16x16x32_bf16 v[108:111], v[152:155], v[192:195], v[108:111]
	v_mfma_f32_16x16x32_bf16 v[104:107], v[160:163], v[192:195], v[104:107]
	v_mfma_f32_16x16x32_bf16 v[92:95], v[152:155], v[200:203], v[92:95]
	v_mfma_f32_16x16x32_bf16 v[88:91], v[160:163], v[200:203], v[88:91]
	v_mfma_f32_16x16x32_bf16 v[76:79], v[152:155], v[208:211], v[76:79]
	v_mfma_f32_16x16x32_bf16 v[72:75], v[160:163], v[208:211], v[72:75]
	v_mfma_f32_16x16x32_bf16 v[120:123], v[156:159], v[188:191], v[120:123]
	v_mfma_f32_16x16x32_bf16 v[124:127], v[164:167], v[188:191], v[124:127]
	v_mfma_f32_16x16x32_bf16 v[108:111], v[156:159], v[196:199], v[108:111]
	v_mfma_f32_16x16x32_bf16 v[104:107], v[164:167], v[196:199], v[104:107]
	v_mfma_f32_16x16x32_bf16 v[92:95], v[156:159], v[204:207], v[92:95]
	v_mfma_f32_16x16x32_bf16 v[88:91], v[164:167], v[204:207], v[88:91]
	v_mfma_f32_16x16x32_bf16 v[76:79], v[156:159], v[212:215], v[76:79]
	v_mfma_f32_16x16x32_bf16 v[72:75], v[164:167], v[212:215], v[72:75]
	s_setprio 0
	s_setprio 1
	v_mfma_f32_16x16x32_bf16 v[116:119], v[168:171], v[184:187], v[116:119]
	v_mfma_f32_16x16x32_bf16 v[112:115], v[176:179], v[184:187], v[112:115]
	v_mfma_f32_16x16x32_bf16 v[100:103], v[168:171], v[192:195], v[100:103]
	v_mfma_f32_16x16x32_bf16 v[96:99], v[176:179], v[192:195], v[96:99]
	v_mfma_f32_16x16x32_bf16 v[84:87], v[168:171], v[200:203], v[84:87]
	v_mfma_f32_16x16x32_bf16 v[80:83], v[176:179], v[200:203], v[80:83]
	v_mfma_f32_16x16x32_bf16 v[68:71], v[168:171], v[208:211], v[68:71]
	v_mfma_f32_16x16x32_bf16 v[64:67], v[176:179], v[208:211], v[64:67]
	v_mfma_f32_16x16x32_bf16 v[116:119], v[172:175], v[188:191], v[116:119]
	v_mfma_f32_16x16x32_bf16 v[112:115], v[180:183], v[188:191], v[112:115]
	v_mfma_f32_16x16x32_bf16 v[100:103], v[172:175], v[196:199], v[100:103]
	v_mfma_f32_16x16x32_bf16 v[96:99], v[180:183], v[196:199], v[96:99]
	v_mfma_f32_16x16x32_bf16 v[84:87], v[172:175], v[204:207], v[84:87]
	v_mfma_f32_16x16x32_bf16 v[80:83], v[180:183], v[204:207], v[80:83]
	v_mfma_f32_16x16x32_bf16 v[68:71], v[172:175], v[212:215], v[68:71]
	v_mfma_f32_16x16x32_bf16 v[64:67], v[180:183], v[212:215], v[64:67]
	s_setprio 0
	s_barrier
	s_add_i32 s100, s71, s18
	s_mov_b32 m0, s100
	ds_read_b128 v[184:187], v151 offset:49152
	ds_read_b128 v[188:191], v151 offset:50176
	ds_read_b128 v[192:195], v151 offset:51200
	ds_read_b128 v[196:199], v151 offset:52224
	ds_read_b128 v[200:203], v151 offset:53248
	ds_read_b128 v[204:207], v151 offset:54272
	ds_read_b128 v[208:211], v151 offset:55296
	ds_read_b128 v[212:215], v151 offset:56320
	global_load_lds_dwordx4 v218, s[72:73]
	s_add_i32 m0, s100, 0x2000
	s_add_i32 s100, s101, s18
	global_load_lds_dwordx4 v219, s[72:73]
	s_mov_b32 m0, s100
	s_nop 0
	global_load_lds_dwordx4 v220, s[72:73]
	s_add_i32 m0, s100, 0x2000
	s_nop 0
	global_load_lds_dwordx4 v221, s[72:73]
	s_mov_b32 m0, s51
	s_nop 0
	global_load_lds_dwordx4 v222, s[28:29]
	s_mov_b32 m0, s52
	s_nop 0
	global_load_lds_dwordx4 v223, s[28:29]
	s_waitcnt vmcnt(8)
	s_waitcnt lgkmcnt(0)
	s_barrier
	s_setprio 1
	s_waitcnt lgkmcnt(0)
	v_mfma_f32_16x16x32_bf16 v[60:63], v[152:155], v[184:187], v[60:63]
	v_mfma_f32_16x16x32_bf16 v[56:59], v[160:163], v[184:187], v[56:59]
	v_mfma_f32_16x16x32_bf16 v[44:47], v[152:155], v[192:195], v[44:47]
	v_mfma_f32_16x16x32_bf16 v[40:43], v[160:163], v[192:195], v[40:43]
	v_mfma_f32_16x16x32_bf16 v[28:31], v[152:155], v[200:203], v[28:31]
	v_mfma_f32_16x16x32_bf16 v[24:27], v[160:163], v[200:203], v[24:27]
	v_mfma_f32_16x16x32_bf16 v[12:15], v[152:155], v[208:211], v[12:15]
	v_mfma_f32_16x16x32_bf16 v[8:11], v[160:163], v[208:211], v[8:11]
	v_mfma_f32_16x16x32_bf16 v[60:63], v[156:159], v[188:191], v[60:63]
	v_mfma_f32_16x16x32_bf16 v[56:59], v[164:167], v[188:191], v[56:59]
	v_mfma_f32_16x16x32_bf16 v[44:47], v[156:159], v[196:199], v[44:47]
	v_mfma_f32_16x16x32_bf16 v[40:43], v[164:167], v[196:199], v[40:43]
	v_mfma_f32_16x16x32_bf16 v[28:31], v[156:159], v[204:207], v[28:31]
	v_mfma_f32_16x16x32_bf16 v[24:27], v[164:167], v[204:207], v[24:27]
	v_mfma_f32_16x16x32_bf16 v[12:15], v[156:159], v[212:215], v[12:15]
	v_mfma_f32_16x16x32_bf16 v[8:11], v[164:167], v[212:215], v[8:11]
	s_setprio 0
	s_setprio 1
	v_mfma_f32_16x16x32_bf16 v[52:55], v[168:171], v[184:187], v[52:55]
	v_mfma_f32_16x16x32_bf16 v[48:51], v[176:179], v[184:187], v[48:51]
	v_mfma_f32_16x16x32_bf16 v[36:39], v[168:171], v[192:195], v[36:39]
	v_mfma_f32_16x16x32_bf16 v[32:35], v[176:179], v[192:195], v[32:35]
	v_mfma_f32_16x16x32_bf16 v[20:23], v[168:171], v[200:203], v[20:23]
	v_mfma_f32_16x16x32_bf16 v[16:19], v[176:179], v[200:203], v[16:19]
	v_mfma_f32_16x16x32_bf16 v[4:7], v[168:171], v[208:211], v[4:7]
	v_mfma_f32_16x16x32_bf16 v[0:3], v[176:179], v[208:211], v[0:3]
	v_mfma_f32_16x16x32_bf16 v[52:55], v[172:175], v[188:191], v[52:55]
	v_mfma_f32_16x16x32_bf16 v[48:51], v[180:183], v[188:191], v[48:51]
	v_mfma_f32_16x16x32_bf16 v[36:39], v[172:175], v[196:199], v[36:39]
	v_mfma_f32_16x16x32_bf16 v[32:35], v[180:183], v[196:199], v[32:35]
	v_mfma_f32_16x16x32_bf16 v[20:23], v[172:175], v[204:207], v[20:23]
	v_mfma_f32_16x16x32_bf16 v[16:19], v[180:183], v[204:207], v[16:19]
	v_mfma_f32_16x16x32_bf16 v[4:7], v[172:175], v[212:215], v[4:7]
	v_mfma_f32_16x16x32_bf16 v[0:3], v[180:183], v[212:215], v[0:3]
	s_setprio 0
	s_barrier
	s_add_u32 s46, s46, 0x100
	s_addc_u32 s47, s47, 0
	s_add_u32 s33, s33, 0x100
	s_addc_u32 s67, s67, 0
	s_cmp_ge_i32 s70, s53
	s_mov_b32 s28, s70
	s_cbranch_scc0 .LBB0_1646
	s_movk_i32 s76, 0x6000

.LBB0_2317:
	v_mov_b32_e32 v127, 0
	s_andn2_b64 vcc, exec, s[36:37]
	v_mov_b32_e32 v126, v127
	v_mov_b32_e32 v125, v127
	v_mov_b32_e32 v124, v127
	v_mov_b32_e32 v123, v127
	v_mov_b32_e32 v122, v127
	v_mov_b32_e32 v121, v127
	v_mov_b32_e32 v120, v127
	v_mov_b32_e32 v111, v127
	v_mov_b32_e32 v110, v127
	v_mov_b32_e32 v109, v127
	v_mov_b32_e32 v108, v127
	v_mov_b32_e32 v107, v127
	v_mov_b32_e32 v106, v127
	v_mov_b32_e32 v105, v127
	v_mov_b32_e32 v104, v127
	v_mov_b32_e32 v95, v127
	v_mov_b32_e32 v94, v127
	v_mov_b32_e32 v93, v127
	v_mov_b32_e32 v92, v127
	v_mov_b32_e32 v91, v127
	v_mov_b32_e32 v90, v127
	v_mov_b32_e32 v89, v127
	v_mov_b32_e32 v88, v127
	v_mov_b32_e32 v79, v127
	v_mov_b32_e32 v78, v127
	v_mov_b32_e32 v77, v127
	v_mov_b32_e32 v76, v127
	v_mov_b32_e32 v75, v127
	v_mov_b32_e32 v74, v127
	v_mov_b32_e32 v73, v127
	v_mov_b32_e32 v72, v127
	v_mov_b32_e32 v119, v127
	v_mov_b32_e32 v118, v127
	v_mov_b32_e32 v117, v127
	v_mov_b32_e32 v116, v127
	v_mov_b32_e32 v115, v127
	v_mov_b32_e32 v114, v127
	v_mov_b32_e32 v113, v127
	v_mov_b32_e32 v112, v127
	v_mov_b32_e32 v103, v127
	v_mov_b32_e32 v102, v127
	v_mov_b32_e32 v101, v127
	v_mov_b32_e32 v100, v127
	v_mov_b32_e32 v99, v127
	v_mov_b32_e32 v98, v127
	v_mov_b32_e32 v97, v127
	v_mov_b32_e32 v96, v127
	v_mov_b32_e32 v87, v127
	v_mov_b32_e32 v86, v127
	v_mov_b32_e32 v85, v127
	v_mov_b32_e32 v84, v127
	v_mov_b32_e32 v83, v127
	v_mov_b32_e32 v82, v127
	v_mov_b32_e32 v81, v127
	v_mov_b32_e32 v80, v127
	v_mov_b32_e32 v71, v127
	v_mov_b32_e32 v70, v127
	v_mov_b32_e32 v69, v127
	v_mov_b32_e32 v68, v127
	v_mov_b32_e32 v67, v127
	v_mov_b32_e32 v66, v127
	v_mov_b32_e32 v65, v127
	v_mov_b32_e32 v64, v127
	v_mov_b32_e32 v63, v127
	v_mov_b32_e32 v62, v127
	v_mov_b32_e32 v61, v127
	v_mov_b32_e32 v60, v127
	v_mov_b32_e32 v59, v127
	v_mov_b32_e32 v58, v127
	v_mov_b32_e32 v57, v127
	v_mov_b32_e32 v56, v127
	v_mov_b32_e32 v47, v127
	v_mov_b32_e32 v46, v127
	v_mov_b32_e32 v45, v127
	v_mov_b32_e32 v44, v127
	v_mov_b32_e32 v43, v127
	v_mov_b32_e32 v42, v127
	v_mov_b32_e32 v41, v127
	v_mov_b32_e32 v40, v127
	v_mov_b32_e32 v31, v127
	v_mov_b32_e32 v30, v127
	v_mov_b32_e32 v29, v127
	v_mov_b32_e32 v28, v127
	v_mov_b32_e32 v27, v127
	v_mov_b32_e32 v26, v127
	v_mov_b32_e32 v25, v127
	v_mov_b32_e32 v24, v127
	v_mov_b32_e32 v15, v127
	v_mov_b32_e32 v14, v127
	v_mov_b32_e32 v13, v127
	v_mov_b32_e32 v12, v127
	v_mov_b32_e32 v11, v127
	v_mov_b32_e32 v10, v127
	v_mov_b32_e32 v9, v127
	v_mov_b32_e32 v8, v127
	v_mov_b32_e32 v55, v127
	v_mov_b32_e32 v54, v127
	v_mov_b32_e32 v53, v127
	v_mov_b32_e32 v52, v127
	v_mov_b32_e32 v51, v127
	v_mov_b32_e32 v50, v127
	v_mov_b32_e32 v49, v127
	v_mov_b32_e32 v48, v127
	v_mov_b32_e32 v39, v127
	v_mov_b32_e32 v38, v127
	v_mov_b32_e32 v37, v127
	v_mov_b32_e32 v36, v127
	v_mov_b32_e32 v35, v127
	v_mov_b32_e32 v34, v127
	v_mov_b32_e32 v33, v127
	v_mov_b32_e32 v32, v127
	v_mov_b32_e32 v23, v127
	v_mov_b32_e32 v22, v127
	v_mov_b32_e32 v21, v127
	v_mov_b32_e32 v20, v127
	v_mov_b32_e32 v19, v127
	v_mov_b32_e32 v18, v127
	v_mov_b32_e32 v17, v127
	v_mov_b32_e32 v16, v127
	v_mov_b32_e32 v7, v127
	v_mov_b32_e32 v6, v127
	v_mov_b32_e32 v5, v127
	v_mov_b32_e32 v4, v127
	v_mov_b32_e32 v3, v127
	v_mov_b32_e32 v2, v127
	v_mov_b32_e32 v1, v127
	v_mov_b32_e32 v0, v127
	s_cbranch_vccnz .LBB0_2320
	s_add_u32 s46, s46, 0x80
	s_addc_u32 s47, s47, 0
	s_add_u32 s33, s28, 0x100
	v_mov_b32_e32 v0, 0
	s_addc_u32 s63, s29, 0
	s_mov_b32 s28, 0
	v_mov_b32_e32 v1, v0
	v_mov_b32_e32 v2, v0
	v_mov_b32_e32 v3, v0
	v_mov_b32_e32 v4, v0
	v_mov_b32_e32 v5, v0
	v_mov_b32_e32 v6, v0
	v_mov_b32_e32 v7, v0
	v_mov_b32_e32 v16, v0
	v_mov_b32_e32 v17, v0
	v_mov_b32_e32 v18, v0
	v_mov_b32_e32 v19, v0
	v_mov_b32_e32 v20, v0
	v_mov_b32_e32 v21, v0
	v_mov_b32_e32 v22, v0
	v_mov_b32_e32 v23, v0
	v_mov_b32_e32 v32, v0
	v_mov_b32_e32 v33, v0
	v_mov_b32_e32 v34, v0
	v_mov_b32_e32 v35, v0
	v_mov_b32_e32 v36, v0
	v_mov_b32_e32 v37, v0
	v_mov_b32_e32 v38, v0
	v_mov_b32_e32 v39, v0
	v_mov_b32_e32 v48, v0
	v_mov_b32_e32 v49, v0
	v_mov_b32_e32 v50, v0
	v_mov_b32_e32 v51, v0
	v_mov_b32_e32 v52, v0
	v_mov_b32_e32 v53, v0
	v_mov_b32_e32 v54, v0
	v_mov_b32_e32 v55, v0
	v_mov_b32_e32 v8, v0
	v_mov_b32_e32 v9, v0
	v_mov_b32_e32 v10, v0
	v_mov_b32_e32 v11, v0
	v_mov_b32_e32 v12, v0
	v_mov_b32_e32 v13, v0
	v_mov_b32_e32 v14, v0
	v_mov_b32_e32 v15, v0
	v_mov_b32_e32 v24, v0
	v_mov_b32_e32 v25, v0
	v_mov_b32_e32 v26, v0
	v_mov_b32_e32 v27, v0
	v_mov_b32_e32 v28, v0
	v_mov_b32_e32 v29, v0
	v_mov_b32_e32 v30, v0
	v_mov_b32_e32 v31, v0
	v_mov_b32_e32 v40, v0
	v_mov_b32_e32 v41, v0
	v_mov_b32_e32 v42, v0
	v_mov_b32_e32 v43, v0
	v_mov_b32_e32 v44, v0
	v_mov_b32_e32 v45, v0
	v_mov_b32_e32 v46, v0
	v_mov_b32_e32 v47, v0
	v_mov_b32_e32 v56, v0
	v_mov_b32_e32 v57, v0
	v_mov_b32_e32 v58, v0
	v_mov_b32_e32 v59, v0
	v_mov_b32_e32 v60, v0
	v_mov_b32_e32 v61, v0
	v_mov_b32_e32 v62, v0
	v_mov_b32_e32 v63, v0
	v_mov_b32_e32 v64, v0
	v_mov_b32_e32 v65, v0
	v_mov_b32_e32 v66, v0
	v_mov_b32_e32 v67, v0
	v_mov_b32_e32 v68, v0
	v_mov_b32_e32 v69, v0
	v_mov_b32_e32 v70, v0
	v_mov_b32_e32 v71, v0
	v_mov_b32_e32 v80, v0
	v_mov_b32_e32 v81, v0
	v_mov_b32_e32 v82, v0
	v_mov_b32_e32 v83, v0
	v_mov_b32_e32 v84, v0
	v_mov_b32_e32 v85, v0
	v_mov_b32_e32 v86, v0
	v_mov_b32_e32 v87, v0
	v_mov_b32_e32 v96, v0
	v_mov_b32_e32 v97, v0
	v_mov_b32_e32 v98, v0
	v_mov_b32_e32 v99, v0
	v_mov_b32_e32 v100, v0
	v_mov_b32_e32 v101, v0
	v_mov_b32_e32 v102, v0
	v_mov_b32_e32 v103, v0
	v_mov_b32_e32 v112, v0
	v_mov_b32_e32 v113, v0
	v_mov_b32_e32 v114, v0
	v_mov_b32_e32 v115, v0
	v_mov_b32_e32 v116, v0
	v_mov_b32_e32 v117, v0
	v_mov_b32_e32 v118, v0
	v_mov_b32_e32 v119, v0
	v_mov_b32_e32 v72, v0
	v_mov_b32_e32 v73, v0
	v_mov_b32_e32 v74, v0
	v_mov_b32_e32 v75, v0
	v_mov_b32_e32 v76, v0
	v_mov_b32_e32 v77, v0
	v_mov_b32_e32 v78, v0
	v_mov_b32_e32 v79, v0
	v_mov_b32_e32 v88, v0
	v_mov_b32_e32 v89, v0
	v_mov_b32_e32 v90, v0
	v_mov_b32_e32 v91, v0
	v_mov_b32_e32 v92, v0
	v_mov_b32_e32 v93, v0
	v_mov_b32_e32 v94, v0
	v_mov_b32_e32 v95, v0
	v_mov_b32_e32 v104, v0
	v_mov_b32_e32 v105, v0
	v_mov_b32_e32 v106, v0
	v_mov_b32_e32 v107, v0
	v_mov_b32_e32 v108, v0
	v_mov_b32_e32 v109, v0
	v_mov_b32_e32 v110, v0
	v_mov_b32_e32 v111, v0
	v_mov_b32_e32 v120, v0
	v_mov_b32_e32 v121, v0
	v_mov_b32_e32 v122, v0
	v_mov_b32_e32 v123, v0
	v_mov_b32_e32 v124, v0
	v_mov_b32_e32 v125, v0
	v_mov_b32_e32 v126, v0
	v_mov_b32_e32 v127, v0
	v_add_u32_e32 v218, s22, v128
	v_add_u32_e32 v219, s22, v136
	v_add_u32_e32 v220, s22, v132
	v_add_u32_e32 v221, s22, v134
	v_add_u32_e32 v222, 128, v128
	v_add_u32_e32 v223, 128, v136
	v_add_u32_e32 v224, 128, v218
	v_add_u32_e32 v225, 128, v219
	v_add_u32_e32 v226, 128, v132
	v_add_u32_e32 v227, 128, v134
.LBB0_2319:
	s_add_i32 s64, s28, 2
	s_add_u32 s65, s46, 0x80
	s_addc_u32 s29, s47, 0
	s_add_i32 s67, 0, 0x10000
	s_cmp_eq_u32 s56, s28
	s_cselect_b32 s29, s41, s29
	s_cselect_b32 s28, s40, s65
	v_add_u32_e32 v161, s67, v153
	s_cselect_b32 s71, s45, s63
	s_cselect_b32 s70, s44, s33
	s_add_i32 s65, 0, 0x14000
	ds_read_b128 v[142:145], v161
	ds_read_b128 v[146:149], v161 offset:1024
	ds_read_b128 v[162:165], v161 offset:2048
	ds_read_b128 v[166:169], v161 offset:3072
	v_add_u32_e32 v161, s65, v153
	ds_read_b128 v[170:173], v161
	ds_read_b128 v[174:177], v161 offset:1024
	ds_read_b128 v[178:181], v161 offset:2048
	ds_read_b128 v[182:185], v161 offset:3072
	s_add_i32 m0, s48, 0xc000
	ds_read_b128 v[186:189], v160
	ds_read_b128 v[190:193], v160 offset:1024
	ds_read_b128 v[194:197], v160 offset:2048
	ds_read_b128 v[198:201], v160 offset:3072
	ds_read_b128 v[202:205], v160 offset:4096
	ds_read_b128 v[206:209], v160 offset:5120
	ds_read_b128 v[210:213], v160 offset:6144
	ds_read_b128 v[214:217], v160 offset:7168
	global_load_lds_dwordx4 v138, s[46:47]
	s_add_i32 m0, s48, 0xe000
	s_nop 0
	global_load_lds_dwordx4 v140, s[46:47]
	s_waitcnt vmcnt(8)
	s_waitcnt lgkmcnt(0)
	s_barrier
	s_setprio 1
	s_waitcnt lgkmcnt(0)
	v_mfma_f32_16x16x32_bf16 v[124:127], v[142:145], v[186:189], v[124:127]
	v_mfma_f32_16x16x32_bf16 v[120:123], v[162:165], v[186:189], v[120:123]
	v_mfma_f32_16x16x32_bf16 v[108:111], v[142:145], v[194:197], v[108:111]
	v_mfma_f32_16x16x32_bf16 v[104:107], v[162:165], v[194:197], v[104:107]
	v_mfma_f32_16x16x32_bf16 v[92:95], v[142:145], v[202:205], v[92:95]
	v_mfma_f32_16x16x32_bf16 v[88:91], v[162:165], v[202:205], v[88:91]
	v_mfma_f32_16x16x32_bf16 v[76:79], v[142:145], v[210:213], v[76:79]
	v_mfma_f32_16x16x32_bf16 v[72:75], v[162:165], v[210:213], v[72:75]
	v_mfma_f32_16x16x32_bf16 v[124:127], v[146:149], v[190:193], v[124:127]
	v_mfma_f32_16x16x32_bf16 v[120:123], v[166:169], v[190:193], v[120:123]
	v_mfma_f32_16x16x32_bf16 v[108:111], v[146:149], v[198:201], v[108:111]
	v_mfma_f32_16x16x32_bf16 v[104:107], v[166:169], v[198:201], v[104:107]
	v_mfma_f32_16x16x32_bf16 v[92:95], v[146:149], v[206:209], v[92:95]
	v_mfma_f32_16x16x32_bf16 v[88:91], v[166:169], v[206:209], v[88:91]
	v_mfma_f32_16x16x32_bf16 v[76:79], v[146:149], v[214:217], v[76:79]
	v_mfma_f32_16x16x32_bf16 v[72:75], v[166:169], v[214:217], v[72:75]
	s_setprio 0
	s_setprio 1
	v_mfma_f32_16x16x32_bf16 v[116:119], v[170:173], v[186:189], v[116:119]
	v_mfma_f32_16x16x32_bf16 v[112:115], v[178:181], v[186:189], v[112:115]
	v_mfma_f32_16x16x32_bf16 v[100:103], v[170:173], v[194:197], v[100:103]
	v_mfma_f32_16x16x32_bf16 v[96:99], v[178:181], v[194:197], v[96:99]
	v_mfma_f32_16x16x32_bf16 v[84:87], v[170:173], v[202:205], v[84:87]
	v_mfma_f32_16x16x32_bf16 v[80:83], v[178:181], v[202:205], v[80:83]
	v_mfma_f32_16x16x32_bf16 v[68:71], v[170:173], v[210:213], v[68:71]
	v_mfma_f32_16x16x32_bf16 v[64:67], v[178:181], v[210:213], v[64:67]
	v_mfma_f32_16x16x32_bf16 v[116:119], v[174:177], v[190:193], v[116:119]
	v_mfma_f32_16x16x32_bf16 v[112:115], v[182:185], v[190:193], v[112:115]
	v_mfma_f32_16x16x32_bf16 v[100:103], v[174:177], v[198:201], v[100:103]
	v_mfma_f32_16x16x32_bf16 v[96:99], v[182:185], v[198:201], v[96:99]
	v_mfma_f32_16x16x32_bf16 v[84:87], v[174:177], v[206:209], v[84:87]
	v_mfma_f32_16x16x32_bf16 v[80:83], v[182:185], v[206:209], v[80:83]
	v_mfma_f32_16x16x32_bf16 v[68:71], v[174:177], v[214:217], v[68:71]
	v_mfma_f32_16x16x32_bf16 v[64:67], v[182:185], v[214:217], v[64:67]
	s_setprio 0
	s_barrier
	s_add_i32 s67, s67, s6
	s_mov_b32 m0, s67
	ds_read_b128 v[186:189], v160 offset:16384
	ds_read_b128 v[190:193], v160 offset:17408
	ds_read_b128 v[194:197], v160 offset:18432
	ds_read_b128 v[198:201], v160 offset:19456
	ds_read_b128 v[202:205], v160 offset:20480
	ds_read_b128 v[206:209], v160 offset:21504
	ds_read_b128 v[210:213], v160 offset:22528
	ds_read_b128 v[214:217], v160 offset:23552
	global_load_lds_dwordx4 v128, s[70:71]
	s_add_i32 m0, s67, 0x2000
	s_add_i32 s65, s65, s6
	global_load_lds_dwordx4 v136, s[70:71]
	s_mov_b32 m0, s65
	s_nop 0
	global_load_lds_dwordx4 v218, s[70:71]
	s_add_i32 m0, s65, 0x2000
	s_nop 0
	global_load_lds_dwordx4 v219, s[70:71]
	s_mov_b32 m0, s48
	s_nop 0
	global_load_lds_dwordx4 v132, s[28:29]
	s_mov_b32 m0, s49
	s_nop 0
	global_load_lds_dwordx4 v134, s[28:29]
	s_waitcnt vmcnt(8)
	s_waitcnt lgkmcnt(0)
	s_barrier
	s_setprio 1
	s_waitcnt lgkmcnt(0)
	v_mfma_f32_16x16x32_bf16 v[60:63], v[142:145], v[186:189], v[60:63]
	v_mfma_f32_16x16x32_bf16 v[56:59], v[162:165], v[186:189], v[56:59]
	v_mfma_f32_16x16x32_bf16 v[44:47], v[142:145], v[194:197], v[44:47]
	v_mfma_f32_16x16x32_bf16 v[40:43], v[162:165], v[194:197], v[40:43]
	v_mfma_f32_16x16x32_bf16 v[28:31], v[142:145], v[202:205], v[28:31]
	v_mfma_f32_16x16x32_bf16 v[24:27], v[162:165], v[202:205], v[24:27]
	v_mfma_f32_16x16x32_bf16 v[12:15], v[142:145], v[210:213], v[12:15]
	v_mfma_f32_16x16x32_bf16 v[8:11], v[162:165], v[210:213], v[8:11]
	v_mfma_f32_16x16x32_bf16 v[60:63], v[146:149], v[190:193], v[60:63]
	v_mfma_f32_16x16x32_bf16 v[56:59], v[166:169], v[190:193], v[56:59]
	v_mfma_f32_16x16x32_bf16 v[44:47], v[146:149], v[198:201], v[44:47]
	v_mfma_f32_16x16x32_bf16 v[40:43], v[166:169], v[198:201], v[40:43]
	v_mfma_f32_16x16x32_bf16 v[28:31], v[146:149], v[206:209], v[28:31]
	v_mfma_f32_16x16x32_bf16 v[24:27], v[166:169], v[206:209], v[24:27]
	v_mfma_f32_16x16x32_bf16 v[12:15], v[146:149], v[214:217], v[12:15]
	v_mfma_f32_16x16x32_bf16 v[8:11], v[166:169], v[214:217], v[8:11]
	s_setprio 0
	s_setprio 1
	v_mfma_f32_16x16x32_bf16 v[52:55], v[170:173], v[186:189], v[52:55]
	v_mfma_f32_16x16x32_bf16 v[48:51], v[178:181], v[186:189], v[48:51]
	v_mfma_f32_16x16x32_bf16 v[36:39], v[170:173], v[194:197], v[36:39]
	v_mfma_f32_16x16x32_bf16 v[32:35], v[178:181], v[194:197], v[32:35]
	v_mfma_f32_16x16x32_bf16 v[20:23], v[170:173], v[202:205], v[20:23]
	v_mfma_f32_16x16x32_bf16 v[16:19], v[178:181], v[202:205], v[16:19]
	v_mfma_f32_16x16x32_bf16 v[4:7], v[170:173], v[210:213], v[4:7]
	v_mfma_f32_16x16x32_bf16 v[0:3], v[178:181], v[210:213], v[0:3]
	v_mfma_f32_16x16x32_bf16 v[52:55], v[174:177], v[190:193], v[52:55]
	v_mfma_f32_16x16x32_bf16 v[48:51], v[182:185], v[190:193], v[48:51]
	v_mfma_f32_16x16x32_bf16 v[36:39], v[174:177], v[198:201], v[36:39]
	v_mfma_f32_16x16x32_bf16 v[32:35], v[182:185], v[198:201], v[32:35]
	v_mfma_f32_16x16x32_bf16 v[20:23], v[174:177], v[206:209], v[20:23]
	v_mfma_f32_16x16x32_bf16 v[16:19], v[182:185], v[206:209], v[16:19]
	v_mfma_f32_16x16x32_bf16 v[4:7], v[174:177], v[214:217], v[4:7]
	v_mfma_f32_16x16x32_bf16 v[0:3], v[182:185], v[214:217], v[0:3]
	s_setprio 0
	s_barrier
	s_add_i32 s65, 0, 0x18000
	v_add_u32_e32 v161, s65, v153
	s_add_i32 s67, 0, 0x1c000
	ds_read_b128 v[142:145], v161
	ds_read_b128 v[146:149], v161 offset:1024
	ds_read_b128 v[162:165], v161 offset:2048
	ds_read_b128 v[166:169], v161 offset:3072
	v_add_u32_e32 v161, s67, v153
	ds_read_b128 v[170:173], v161
	ds_read_b128 v[174:177], v161 offset:1024
	ds_read_b128 v[178:181], v161 offset:2048
	ds_read_b128 v[182:185], v161 offset:3072
	s_mov_b32 m0, s50
	ds_read_b128 v[186:189], v160 offset:32768
	ds_read_b128 v[190:193], v160 offset:33792
	ds_read_b128 v[194:197], v160 offset:34816
	ds_read_b128 v[198:201], v160 offset:35840
	ds_read_b128 v[202:205], v160 offset:36864
	ds_read_b128 v[206:209], v160 offset:37888
	ds_read_b128 v[210:213], v160 offset:38912
	ds_read_b128 v[214:217], v160 offset:39936
	global_load_lds_dwordx4 v220, s[28:29]
	s_mov_b32 m0, s51
	s_nop 0
	global_load_lds_dwordx4 v221, s[28:29]
	s_waitcnt vmcnt(8)
	s_waitcnt lgkmcnt(0)
	s_barrier
	s_setprio 1
	s_waitcnt lgkmcnt(0)
	v_mfma_f32_16x16x32_bf16 v[124:127], v[142:145], v[186:189], v[124:127]
	v_mfma_f32_16x16x32_bf16 v[120:123], v[162:165], v[186:189], v[120:123]
	v_mfma_f32_16x16x32_bf16 v[108:111], v[142:145], v[194:197], v[108:111]
	v_mfma_f32_16x16x32_bf16 v[104:107], v[162:165], v[194:197], v[104:107]
	v_mfma_f32_16x16x32_bf16 v[92:95], v[142:145], v[202:205], v[92:95]
	v_mfma_f32_16x16x32_bf16 v[88:91], v[162:165], v[202:205], v[88:91]
	v_mfma_f32_16x16x32_bf16 v[76:79], v[142:145], v[210:213], v[76:79]
	v_mfma_f32_16x16x32_bf16 v[72:75], v[162:165], v[210:213], v[72:75]
	v_mfma_f32_16x16x32_bf16 v[124:127], v[146:149], v[190:193], v[124:127]
	v_mfma_f32_16x16x32_bf16 v[120:123], v[166:169], v[190:193], v[120:123]
	v_mfma_f32_16x16x32_bf16 v[108:111], v[146:149], v[198:201], v[108:111]
	v_mfma_f32_16x16x32_bf16 v[104:107], v[166:169], v[198:201], v[104:107]
	v_mfma_f32_16x16x32_bf16 v[92:95], v[146:149], v[206:209], v[92:95]
	v_mfma_f32_16x16x32_bf16 v[88:91], v[166:169], v[206:209], v[88:91]
	v_mfma_f32_16x16x32_bf16 v[76:79], v[146:149], v[214:217], v[76:79]
	v_mfma_f32_16x16x32_bf16 v[72:75], v[166:169], v[214:217], v[72:75]
	s_setprio 0
	s_setprio 1
	v_mfma_f32_16x16x32_bf16 v[116:119], v[170:173], v[186:189], v[116:119]
	v_mfma_f32_16x16x32_bf16 v[112:115], v[178:181], v[186:189], v[112:115]
	v_mfma_f32_16x16x32_bf16 v[100:103], v[170:173], v[194:197], v[100:103]
	v_mfma_f32_16x16x32_bf16 v[96:99], v[178:181], v[194:197], v[96:99]
	v_mfma_f32_16x16x32_bf16 v[84:87], v[170:173], v[202:205], v[84:87]
	v_mfma_f32_16x16x32_bf16 v[80:83], v[178:181], v[202:205], v[80:83]
	v_mfma_f32_16x16x32_bf16 v[68:71], v[170:173], v[210:213], v[68:71]
	v_mfma_f32_16x16x32_bf16 v[64:67], v[178:181], v[210:213], v[64:67]
	v_mfma_f32_16x16x32_bf16 v[116:119], v[174:177], v[190:193], v[116:119]
	v_mfma_f32_16x16x32_bf16 v[112:115], v[182:185], v[190:193], v[112:115]
	v_mfma_f32_16x16x32_bf16 v[100:103], v[174:177], v[198:201], v[100:103]
	v_mfma_f32_16x16x32_bf16 v[96:99], v[182:185], v[198:201], v[96:99]
	v_mfma_f32_16x16x32_bf16 v[84:87], v[174:177], v[206:209], v[84:87]
	v_mfma_f32_16x16x32_bf16 v[80:83], v[182:185], v[206:209], v[80:83]
	v_mfma_f32_16x16x32_bf16 v[68:71], v[174:177], v[214:217], v[68:71]
	v_mfma_f32_16x16x32_bf16 v[64:67], v[182:185], v[214:217], v[64:67]
	s_setprio 0
	s_barrier
	s_add_i32 s100, s65, s6
	s_mov_b32 m0, s100
	ds_read_b128 v[186:189], v160 offset:49152
	ds_read_b128 v[190:193], v160 offset:50176
	ds_read_b128 v[194:197], v160 offset:51200
	ds_read_b128 v[198:201], v160 offset:52224
	ds_read_b128 v[202:205], v160 offset:53248
	ds_read_b128 v[206:209], v160 offset:54272
	ds_read_b128 v[210:213], v160 offset:55296
	ds_read_b128 v[214:217], v160 offset:56320
	global_load_lds_dwordx4 v222, s[70:71]
	s_add_i32 m0, s100, 0x2000
	s_add_i32 s100, s67, s6
	global_load_lds_dwordx4 v223, s[70:71]
	s_mov_b32 m0, s100
	s_nop 0
	global_load_lds_dwordx4 v224, s[70:71]
	s_add_i32 m0, s100, 0x2000
	s_nop 0
	global_load_lds_dwordx4 v225, s[70:71]
	s_mov_b32 m0, s52
	s_nop 0
	global_load_lds_dwordx4 v226, s[28:29]
	s_mov_b32 m0, s53
	s_nop 0
	global_load_lds_dwordx4 v227, s[28:29]
	s_waitcnt vmcnt(8)
	s_waitcnt lgkmcnt(0)
	s_barrier
	s_setprio 1
	s_waitcnt lgkmcnt(0)
	v_mfma_f32_16x16x32_bf16 v[60:63], v[142:145], v[186:189], v[60:63]
	v_mfma_f32_16x16x32_bf16 v[56:59], v[162:165], v[186:189], v[56:59]
	v_mfma_f32_16x16x32_bf16 v[44:47], v[142:145], v[194:197], v[44:47]
	v_mfma_f32_16x16x32_bf16 v[40:43], v[162:165], v[194:197], v[40:43]
	v_mfma_f32_16x16x32_bf16 v[28:31], v[142:145], v[202:205], v[28:31]
	v_mfma_f32_16x16x32_bf16 v[24:27], v[162:165], v[202:205], v[24:27]
	v_mfma_f32_16x16x32_bf16 v[12:15], v[142:145], v[210:213], v[12:15]
	v_mfma_f32_16x16x32_bf16 v[8:11], v[162:165], v[210:213], v[8:11]
	v_mfma_f32_16x16x32_bf16 v[60:63], v[146:149], v[190:193], v[60:63]
	v_mfma_f32_16x16x32_bf16 v[56:59], v[166:169], v[190:193], v[56:59]
	v_mfma_f32_16x16x32_bf16 v[44:47], v[146:149], v[198:201], v[44:47]
	v_mfma_f32_16x16x32_bf16 v[40:43], v[166:169], v[198:201], v[40:43]
	v_mfma_f32_16x16x32_bf16 v[28:31], v[146:149], v[206:209], v[28:31]
	v_mfma_f32_16x16x32_bf16 v[24:27], v[166:169], v[206:209], v[24:27]
	v_mfma_f32_16x16x32_bf16 v[12:15], v[146:149], v[214:217], v[12:15]
	v_mfma_f32_16x16x32_bf16 v[8:11], v[166:169], v[214:217], v[8:11]
	s_setprio 0
	s_setprio 1
	v_mfma_f32_16x16x32_bf16 v[52:55], v[170:173], v[186:189], v[52:55]
	v_mfma_f32_16x16x32_bf16 v[48:51], v[178:181], v[186:189], v[48:51]
	v_mfma_f32_16x16x32_bf16 v[36:39], v[170:173], v[194:197], v[36:39]
	v_mfma_f32_16x16x32_bf16 v[32:35], v[178:181], v[194:197], v[32:35]
	v_mfma_f32_16x16x32_bf16 v[20:23], v[170:173], v[202:205], v[20:23]
	v_mfma_f32_16x16x32_bf16 v[16:19], v[178:181], v[202:205], v[16:19]
	v_mfma_f32_16x16x32_bf16 v[4:7], v[170:173], v[210:213], v[4:7]
	v_mfma_f32_16x16x32_bf16 v[0:3], v[178:181], v[210:213], v[0:3]
	v_mfma_f32_16x16x32_bf16 v[52:55], v[174:177], v[190:193], v[52:55]
	v_mfma_f32_16x16x32_bf16 v[48:51], v[182:185], v[190:193], v[48:51]
	v_mfma_f32_16x16x32_bf16 v[36:39], v[174:177], v[198:201], v[36:39]
	v_mfma_f32_16x16x32_bf16 v[32:35], v[182:185], v[198:201], v[32:35]
	v_mfma_f32_16x16x32_bf16 v[20:23], v[174:177], v[206:209], v[20:23]
	v_mfma_f32_16x16x32_bf16 v[16:19], v[182:185], v[206:209], v[16:19]
	v_mfma_f32_16x16x32_bf16 v[4:7], v[174:177], v[214:217], v[4:7]
	v_mfma_f32_16x16x32_bf16 v[0:3], v[182:185], v[214:217], v[0:3]
	s_setprio 0
	s_barrier
	s_add_u32 s46, s46, 0x100
	s_addc_u32 s47, s47, 0
	s_add_u32 s33, s33, 0x100
	s_addc_u32 s63, s63, 0
	s_cmp_ge_i32 s64, s20
	s_mov_b32 s28, s64
	s_cbranch_scc0 .LBB0_2319
